# A+Q+P2 + swiglu epilogue silu(a)*b with packed f32 mul/add around per-element exp/rcp (19 fewer VALU per 16 outputs)
# speedup vs baseline: 1.0043x; 1.0043x over previous
; __device__ __forceinline__ unsigned cvt_pk_bf16(float lo, float hi) { unsigned r; asm volatile("v_cvt_pk_bf16_f32 %0, %1, %2" : "=v"(r) : "v"(lo), "v"(hi)); return r; }
; __device__ __forceinline__ float row_rstd(const float* ss, int row) { return 1.0f / sqrtf(ss[row] * (1.0f / DM) + 1e-6f); }
; __device__ __forceinline__ float silu_mul(float a, float b) { return a * b * __builtin_amdgcn_rcpf(1.0f + __builtin_amdgcn_exp2f(-a * LOG2E)); }
;     __device__ __forceinline__ void operator()(const f32x4 (&acc)[2][2][4][2], const Unit& u, int wr, int wc, int fr, int fq) const {
;         const int row0 = u.pm * BM + wr * 64 + fr, col0 = u.pn * HALF + wc * 32 + 8 * fq;
;         const int s = (u.pm < ML / BM) ? (u.pm >> 5) : 4;
;         const float* bp = bias + (size_t)s * BIAS_N + u.pn * BM + wc * 32 + 8 * fq;
;         const f32x4 ba0 = *(const f32x4*)bp, ba1 = *(const f32x4*)(bp + 4), bb0 = *(const f32x4*)(bp + HALF), bb1 = *(const f32x4*)(bp + HALF + 4);
;         const int lane = fq * 16 + fr;
;         const float rsl0 = row_rstd(ss, u.pm * BM + wr * 64 + lane), rsl1 = row_rstd(ss, u.pm * BM + HALF + wr * 64 + lane);
; #pragma unroll
;         for (int ai = 0; ai < 2; ++ai)
; #pragma unroll
;             for (int m = 0; m < 4; ++m) { const int row = row0 + ai * HALF + m * 16; const float rs = __shfl(ai ? rsl1 : rsl0, m * 16 + fr); bf16_t* rowp = O + (size_t)row * DFF + col0;
;                 const f32x4 a0 = acc[ai][0][m][0] * rs + ba0, a1 = acc[ai][0][m][1] * rs + ba1, b0 = acc[ai][1][m][0] * rs + bb0, b1 = acc[ai][1][m][1] * rs + bb1;
;                 u32x4 w; w.x = cvt_pk_bf16(silu_mul(a0[0], b0[0]), silu_mul(a0[1], b0[1])); w.y = cvt_pk_bf16(silu_mul(a0[2], b0[2]), silu_mul(a0[3], b0[3]));
;                 w.z = cvt_pk_bf16(silu_mul(a1[0], b1[0]), silu_mul(a1[1], b1[1])); w.w = cvt_pk_bf16(silu_mul(a1[2], b1[2]), silu_mul(a1[3], b1[3]));
;                 *(u32x4*)rowp = w; }
.LBB0_193:
	s_lshl_b32 s2, s2, 8
	s_add_i32 s12, s2, s54
	s_lshl_b64 s[2:3], s[16:17], 2
	s_add_u32 s13, s68, s2
	s_addc_u32 s14, s69, s3
	s_lshl_b32 s2, s0, 8
	s_ashr_i32 s3, s2, 31
	s_lshl_b64 s[2:3], s[2:3], 2
	v_lshl_or_b32 v164, s0, 7, v173
	s_add_u32 s0, s13, s2
	s_addc_u32 s3, s14, s3
	v_or_b32_e32 v162, s12, v171
	s_add_u32 s2, s0, s60
	v_ashrrev_i32_e32 v163, 31, v162
	s_addc_u32 s3, s3, 0
	v_lshl_add_u64 v[162:163], v[162:163], 2, s[8:9]
	v_mov_b32_e32 v74, v234
	v_mov_b32_e32 v75, v235
	v_mov_b32_e32 v76, v236
	v_mov_b32_e32 v77, v237
	v_mov_b32_e32 v78, v238
	v_mov_b32_e32 v79, v239
	v_mov_b32_e32 v80, v240
	v_mov_b32_e32 v81, v241
	v_mov_b32_e32 v66, v242
	v_mov_b32_e32 v67, v243
	v_mov_b32_e32 v68, v244
	v_mov_b32_e32 v69, v245
	v_mov_b32_e32 v70, v246
	v_mov_b32_e32 v71, v247
	v_mov_b32_e32 v72, v248
	v_mov_b32_e32 v73, v249
	v_or_b32_e32 v181, s12, v169
	v_mov_b32_e32 v162, v250
	s_waitcnt vmcnt(0)
	v_fmamk_f32 v162, v162, 0x3a000000, v178
	v_cmp_gt_f32_e32 vcc, s61, v162
	v_mul_f32_e32 v163, 0x4f800000, v162
	s_nop 0
	v_cndmask_b32_e32 v162, v162, v163, vcc
	v_sqrt_f32_e32 v163, v162
	s_nop 0
	v_add_u32_e32 v165, -1, v163
	v_fma_f32 v166, -v165, v163, v162
	v_cmp_ge_f32_e64 s[2:3], 0, v166
	v_add_u32_e32 v166, 1, v163
	s_nop 0
	v_cndmask_b32_e64 v165, v163, v165, s[2:3]
	v_fma_f32 v163, -v166, v163, v162
	v_cmp_lt_f32_e64 s[2:3], 0, v163
	s_nop 1
	v_cndmask_b32_e64 v163, v165, v166, s[2:3]
	v_mul_f32_e32 v165, 0x37800000, v163
	v_cndmask_b32_e32 v163, v163, v165, vcc
	v_cmp_class_f32_e32 vcc, v162, v179
	s_nop 1
	v_cndmask_b32_e32 v166, v163, v162, vcc
	v_add_u32_e32 v162, s12, v172
	v_ashrrev_i32_e32 v163, 31, v162
	v_lshl_add_u64 v[162:163], v[162:163], 2, s[8:9]
	v_mov_b32_e32 v162, v251
	v_fmamk_f32 v162, v162, 0x3a000000, v178
	v_cmp_gt_f32_e32 vcc, s61, v162
	v_mul_f32_e32 v163, 0x4f800000, v162
	s_nop 0
	v_cndmask_b32_e32 v162, v162, v163, vcc
	v_sqrt_f32_e32 v163, v162
	s_nop 0
	v_add_u32_e32 v165, -1, v163
	v_fma_f32 v167, -v165, v163, v162
	v_cmp_ge_f32_e64 s[2:3], 0, v167
	v_add_u32_e32 v167, 1, v163
	s_nop 0
	v_cndmask_b32_e64 v165, v163, v165, s[2:3]
	v_fma_f32 v163, -v167, v163, v162
	v_cmp_lt_f32_e64 s[2:3], 0, v163
	s_nop 1
	v_cndmask_b32_e64 v163, v165, v167, s[2:3]
	v_mul_f32_e32 v165, 0x37800000, v163
	v_cndmask_b32_e32 v163, v163, v165, vcc
	v_cmp_class_f32_e32 vcc, v162, v179
	v_ashrrev_i32_e32 v165, 31, v164
	v_lshlrev_b64 v[164:165], 1, v[164:165]
	v_cndmask_b32_e32 v182, v163, v162, vcc
	v_div_scale_f32 v162, s[2:3], v166, v166, 1.0
	v_rcp_f32_e32 v163, v162
	s_nop 0
	v_fma_f32 v167, -v162, v163, 1.0
	v_fmac_f32_e32 v163, v167, v163
	v_div_scale_f32 v167, vcc, 1.0, v166, 1.0
	v_mul_f32_e32 v168, v167, v163
	v_fma_f32 v183, -v162, v168, v167
	v_fmac_f32_e32 v168, v183, v163
	v_fma_f32 v162, -v162, v168, v167
	v_div_fmas_f32 v162, v162, v163, v168
	v_div_fixup_f32 v183, v162, v166, 1.0
	s_mov_b32 s100, 0xbfb8aa3b
	ds_bpermute_b32 v168, v180, v183
	v_mov_b64_e32 v[162:163], s[96:97]
	v_mad_i64_i32 v[166:167], s[2:3], v181, s59, v[162:163]
	v_lshl_add_u64 v[166:167], v[166:167], 0, v[164:165]
	s_waitcnt lgkmcnt(0)
	v_pk_fma_f32 v[142:143], v[142:143], v[168:169], v[78:79] op_sel_hi:[1,0,1]
	v_pk_fma_f32 v[144:145], v[144:145], v[168:169], v[80:81] op_sel_hi:[1,0,1]
	v_pk_fma_f32 v[134:135], v[134:135], v[168:169], v[70:71] op_sel_hi:[1,0,1]
	v_pk_fma_f32 v[136:137], v[136:137], v[168:169], v[72:73] op_sel_hi:[1,0,1]
	v_pk_fma_f32 v[138:139], v[138:139], v[168:169], v[74:75] op_sel_hi:[1,0,1]
	v_pk_fma_f32 v[140:141], v[140:141], v[168:169], v[76:77] op_sel_hi:[1,0,1]
	v_pk_fma_f32 v[130:131], v[130:131], v[168:169], v[66:67] op_sel_hi:[1,0,1]
	v_pk_fma_f32 v[132:133], v[132:133], v[168:169], v[68:69] op_sel_hi:[1,0,1]
	v_pk_mul_f32 v[234:235], v[142:143], s[100:101] op_sel_hi:[1,0]
	v_pk_mul_f32 v[236:237], v[144:145], s[100:101] op_sel_hi:[1,0]
	v_exp_f32_e32 v234, v234
	v_exp_f32_e32 v235, v235
	v_exp_f32_e32 v236, v236
	v_exp_f32_e32 v237, v237
	v_pk_add_f32 v[234:235], v[234:235], 1.0 op_sel_hi:[1,0]
	v_pk_add_f32 v[236:237], v[236:237], 1.0 op_sel_hi:[1,0]
	v_rcp_f32_e32 v234, v234
	v_rcp_f32_e32 v235, v235
	v_rcp_f32_e32 v236, v236
	v_rcp_f32_e32 v237, v237
	v_pk_mul_f32 v[134:135], v[142:143], v[134:135]
	v_pk_mul_f32 v[136:137], v[144:145], v[136:137]
	v_pk_mul_f32 v[134:135], v[134:135], v[234:235]
	v_pk_mul_f32 v[136:137], v[136:137], v[236:237]
	v_cvt_pk_bf16_f32 v238, v134, v135
	v_cvt_pk_bf16_f32 v239, v136, v137
	v_pk_mul_f32 v[234:235], v[138:139], s[100:101] op_sel_hi:[1,0]
	v_pk_mul_f32 v[236:237], v[140:141], s[100:101] op_sel_hi:[1,0]
	v_exp_f32_e32 v234, v234
	v_exp_f32_e32 v235, v235
	v_exp_f32_e32 v236, v236
	v_exp_f32_e32 v237, v237
	v_pk_add_f32 v[234:235], v[234:235], 1.0 op_sel_hi:[1,0]
	v_pk_add_f32 v[236:237], v[236:237], 1.0 op_sel_hi:[1,0]
	v_rcp_f32_e32 v234, v234
	v_rcp_f32_e32 v235, v235
	v_rcp_f32_e32 v236, v236
	v_rcp_f32_e32 v237, v237
	v_pk_mul_f32 v[130:131], v[138:139], v[130:131]
	v_pk_mul_f32 v[132:133], v[140:141], v[132:133]
	v_pk_mul_f32 v[130:131], v[130:131], v[234:235]
	v_pk_mul_f32 v[132:133], v[132:133], v[236:237]
	v_cvt_pk_bf16_f32 v240, v130, v131
	v_cvt_pk_bf16_f32 v241, v132, v133
	global_store_dwordx4 v[166:167], v[238:241], off
	ds_bpermute_b32 v130, v180, v183 offset:64
	v_or_b32_e32 v131, 16, v181
	v_mad_i64_i32 v[132:133], s[2:3], v131, s59, v[162:163]
	s_waitcnt lgkmcnt(0)
; __device__ __forceinline__ unsigned cvt_pk_bf16(float lo, float hi) { unsigned r; asm volatile("v_cvt_pk_bf16_f32 %0, %1, %2" : "=v"(r) : "v"(lo), "v"(hi)); return r; }
; __device__ __forceinline__ float silu_mul(float a, float b) { return a * b * __builtin_amdgcn_rcpf(1.0f + __builtin_amdgcn_exp2f(-a * LOG2E)); }
;     __device__ __forceinline__ void operator()(const f32x4 (&acc)[2][2][4][2], const Unit& u, int wr, int wc, int fr, int fq) const {
;     ...
;             for (int m = 0; m < 4; ++m) { const int row = row0 + ai * HALF + m * 16; const float rs = __shfl(ai ? rsl1 : rsl0, m * 16 + fr); bf16_t* rowp = O + (size_t)row * DFF + col0;
;                 const f32x4 a0 = acc[ai][0][m][0] * rs + ba0, a1 = acc[ai][0][m][1] * rs + ba1, b0 = acc[ai][1][m][0] * rs + bb0, b1 = acc[ai][1][m][1] * rs + bb1;
;                 u32x4 w; w.x = cvt_pk_bf16(silu_mul(a0[0], b0[0]), silu_mul(a0[1], b0[1])); w.y = cvt_pk_bf16(silu_mul(a0[2], b0[2]), silu_mul(a0[3], b0[3]));
;                 w.z = cvt_pk_bf16(silu_mul(a1[0], b1[0]), silu_mul(a1[1], b1[1])); w.w = cvt_pk_bf16(silu_mul(a1[2], b1[2]), silu_mul(a1[3], b1[3]));
;                 *(u32x4*)rowp = w; }
	v_lshl_add_u64 v[132:133], v[132:133], 0, v[164:165]
	v_pk_fma_f32 v[126:127], v[126:127], v[130:131], v[78:79] op_sel_hi:[1,0,1]
	v_pk_fma_f32 v[128:129], v[128:129], v[130:131], v[80:81] op_sel_hi:[1,0,1]
	v_pk_fma_f32 v[118:119], v[118:119], v[130:131], v[70:71] op_sel_hi:[1,0,1]
	v_pk_fma_f32 v[120:121], v[120:121], v[130:131], v[72:73] op_sel_hi:[1,0,1]
	v_pk_fma_f32 v[122:123], v[122:123], v[130:131], v[74:75] op_sel_hi:[1,0,1]
	v_pk_fma_f32 v[124:125], v[124:125], v[130:131], v[76:77] op_sel_hi:[1,0,1]
	v_pk_fma_f32 v[114:115], v[114:115], v[130:131], v[66:67] op_sel_hi:[1,0,1]
	v_pk_fma_f32 v[116:117], v[116:117], v[130:131], v[68:69] op_sel_hi:[1,0,1]
	v_pk_mul_f32 v[234:235], v[126:127], s[100:101] op_sel_hi:[1,0]
	v_pk_mul_f32 v[236:237], v[128:129], s[100:101] op_sel_hi:[1,0]
	v_exp_f32_e32 v234, v234
	v_exp_f32_e32 v235, v235
	v_exp_f32_e32 v236, v236
	v_exp_f32_e32 v237, v237
	v_pk_add_f32 v[234:235], v[234:235], 1.0 op_sel_hi:[1,0]
	v_pk_add_f32 v[236:237], v[236:237], 1.0 op_sel_hi:[1,0]
	v_rcp_f32_e32 v234, v234
	v_rcp_f32_e32 v235, v235
	v_rcp_f32_e32 v236, v236
	v_rcp_f32_e32 v237, v237
	v_pk_mul_f32 v[118:119], v[126:127], v[118:119]
	v_pk_mul_f32 v[120:121], v[128:129], v[120:121]
	v_pk_mul_f32 v[118:119], v[118:119], v[234:235]
	v_pk_mul_f32 v[120:121], v[120:121], v[236:237]
	v_cvt_pk_bf16_f32 v238, v118, v119
	v_cvt_pk_bf16_f32 v239, v120, v121
	v_pk_mul_f32 v[234:235], v[122:123], s[100:101] op_sel_hi:[1,0]
	v_pk_mul_f32 v[236:237], v[124:125], s[100:101] op_sel_hi:[1,0]
	v_exp_f32_e32 v234, v234
	v_exp_f32_e32 v235, v235
	v_exp_f32_e32 v236, v236
	v_exp_f32_e32 v237, v237
	v_pk_add_f32 v[234:235], v[234:235], 1.0 op_sel_hi:[1,0]
	v_pk_add_f32 v[236:237], v[236:237], 1.0 op_sel_hi:[1,0]
	v_rcp_f32_e32 v234, v234
	v_rcp_f32_e32 v235, v235
	v_rcp_f32_e32 v236, v236
	v_rcp_f32_e32 v237, v237
	v_pk_mul_f32 v[114:115], v[122:123], v[114:115]
	v_pk_mul_f32 v[116:117], v[124:125], v[116:117]
	v_pk_mul_f32 v[114:115], v[114:115], v[234:235]
	v_pk_mul_f32 v[116:117], v[116:117], v[236:237]
	v_cvt_pk_bf16_f32 v240, v114, v115
	v_cvt_pk_bf16_f32 v241, v116, v117
	global_store_dwordx4 v[132:133], v[238:241], off
	ds_bpermute_b32 v114, v180, v183 offset:128
	v_or_b32_e32 v115, 32, v181
	v_mad_i64_i32 v[116:117], s[2:3], v115, s59, v[162:163]
	s_waitcnt lgkmcnt(0)
	v_lshl_add_u64 v[116:117], v[116:117], 0, v[164:165]
	v_pk_fma_f32 v[110:111], v[110:111], v[114:115], v[78:79] op_sel_hi:[1,0,1]
	v_pk_fma_f32 v[112:113], v[112:113], v[114:115], v[80:81] op_sel_hi:[1,0,1]
	v_pk_fma_f32 v[102:103], v[102:103], v[114:115], v[70:71] op_sel_hi:[1,0,1]
	v_pk_fma_f32 v[104:105], v[104:105], v[114:115], v[72:73] op_sel_hi:[1,0,1]
	v_pk_fma_f32 v[106:107], v[106:107], v[114:115], v[74:75] op_sel_hi:[1,0,1]
	v_pk_fma_f32 v[108:109], v[108:109], v[114:115], v[76:77] op_sel_hi:[1,0,1]
	v_pk_fma_f32 v[98:99], v[98:99], v[114:115], v[66:67] op_sel_hi:[1,0,1]
	v_pk_fma_f32 v[100:101], v[100:101], v[114:115], v[68:69] op_sel_hi:[1,0,1]
	v_pk_mul_f32 v[234:235], v[110:111], s[100:101] op_sel_hi:[1,0]
	v_pk_mul_f32 v[236:237], v[112:113], s[100:101] op_sel_hi:[1,0]
	v_exp_f32_e32 v234, v234
	v_exp_f32_e32 v235, v235
	v_exp_f32_e32 v236, v236
	v_exp_f32_e32 v237, v237
	v_pk_add_f32 v[234:235], v[234:235], 1.0 op_sel_hi:[1,0]
	v_pk_add_f32 v[236:237], v[236:237], 1.0 op_sel_hi:[1,0]
	v_rcp_f32_e32 v234, v234
	v_rcp_f32_e32 v235, v235
	v_rcp_f32_e32 v236, v236
	v_rcp_f32_e32 v237, v237
	v_pk_mul_f32 v[102:103], v[110:111], v[102:103]
	v_pk_mul_f32 v[104:105], v[112:113], v[104:105]
	v_pk_mul_f32 v[102:103], v[102:103], v[234:235]
	v_pk_mul_f32 v[104:105], v[104:105], v[236:237]
	v_cvt_pk_bf16_f32 v238, v102, v103
	v_cvt_pk_bf16_f32 v239, v104, v105
	v_pk_mul_f32 v[234:235], v[106:107], s[100:101] op_sel_hi:[1,0]
	v_pk_mul_f32 v[236:237], v[108:109], s[100:101] op_sel_hi:[1,0]
	v_exp_f32_e32 v234, v234
	v_exp_f32_e32 v235, v235
	v_exp_f32_e32 v236, v236
	v_exp_f32_e32 v237, v237
	v_pk_add_f32 v[234:235], v[234:235], 1.0 op_sel_hi:[1,0]
	v_pk_add_f32 v[236:237], v[236:237], 1.0 op_sel_hi:[1,0]
	v_rcp_f32_e32 v234, v234
	v_rcp_f32_e32 v235, v235
	v_rcp_f32_e32 v236, v236
	v_rcp_f32_e32 v237, v237
	v_pk_mul_f32 v[98:99], v[106:107], v[98:99]
	v_pk_mul_f32 v[100:101], v[108:109], v[100:101]
	v_pk_mul_f32 v[98:99], v[98:99], v[234:235]
	v_pk_mul_f32 v[100:101], v[100:101], v[236:237]
	v_cvt_pk_bf16_f32 v240, v98, v99
	v_cvt_pk_bf16_f32 v241, v100, v101
	global_store_dwordx4 v[116:117], v[238:241], off
	ds_bpermute_b32 v98, v180, v183 offset:192
	v_or_b32_e32 v99, 48, v181
	v_mad_i64_i32 v[100:101], s[2:3], v99, s59, v[162:163]
	s_waitcnt lgkmcnt(0)
; __device__ __forceinline__ unsigned cvt_pk_bf16(float lo, float hi) { unsigned r; asm volatile("v_cvt_pk_bf16_f32 %0, %1, %2" : "=v"(r) : "v"(lo), "v"(hi)); return r; }
; __device__ __forceinline__ float row_rstd(const float* ss, int row) { return 1.0f / sqrtf(ss[row] * (1.0f / DM) + 1e-6f); }
; __device__ __forceinline__ float silu_mul(float a, float b) { return a * b * __builtin_amdgcn_rcpf(1.0f + __builtin_amdgcn_exp2f(-a * LOG2E)); }
;     __device__ __forceinline__ void operator()(const f32x4 (&acc)[2][2][4][2], const Unit& u, int wr, int wc, int fr, int fq) const {
;     ...
;         const float rsl0 = row_rstd(ss, u.pm * BM + wr * 64 + lane), rsl1 = row_rstd(ss, u.pm * BM + HALF + wr * 64 + lane);
; #pragma unroll
;         for (int ai = 0; ai < 2; ++ai)
; #pragma unroll
;             for (int m = 0; m < 4; ++m) { const int row = row0 + ai * HALF + m * 16; const float rs = __shfl(ai ? rsl1 : rsl0, m * 16 + fr); bf16_t* rowp = O + (size_t)row * DFF + col0;
;                 const f32x4 a0 = acc[ai][0][m][0] * rs + ba0, a1 = acc[ai][0][m][1] * rs + ba1, b0 = acc[ai][1][m][0] * rs + bb0, b1 = acc[ai][1][m][1] * rs + bb1;
;                 u32x4 w; w.x = cvt_pk_bf16(silu_mul(a0[0], b0[0]), silu_mul(a0[1], b0[1])); w.y = cvt_pk_bf16(silu_mul(a0[2], b0[2]), silu_mul(a0[3], b0[3]));
;                 w.z = cvt_pk_bf16(silu_mul(a1[0], b1[0]), silu_mul(a1[1], b1[1])); w.w = cvt_pk_bf16(silu_mul(a1[2], b1[2]), silu_mul(a1[3], b1[3]));
;                 *(u32x4*)rowp = w; }
	v_lshl_add_u64 v[100:101], v[100:101], 0, v[164:165]
	v_pk_fma_f32 v[94:95], v[94:95], v[98:99], v[78:79] op_sel_hi:[1,0,1]
	v_pk_fma_f32 v[96:97], v[96:97], v[98:99], v[80:81] op_sel_hi:[1,0,1]
	v_pk_fma_f32 v[86:87], v[86:87], v[98:99], v[70:71] op_sel_hi:[1,0,1]
	v_pk_fma_f32 v[88:89], v[88:89], v[98:99], v[72:73] op_sel_hi:[1,0,1]
	v_pk_fma_f32 v[90:91], v[90:91], v[98:99], v[74:75] op_sel_hi:[1,0,1]
	v_pk_fma_f32 v[92:93], v[92:93], v[98:99], v[76:77] op_sel_hi:[1,0,1]
	v_pk_fma_f32 v[82:83], v[82:83], v[98:99], v[66:67] op_sel_hi:[1,0,1]
	v_pk_fma_f32 v[84:85], v[84:85], v[98:99], v[68:69] op_sel_hi:[1,0,1]
	v_pk_mul_f32 v[234:235], v[94:95], s[100:101] op_sel_hi:[1,0]
	v_pk_mul_f32 v[236:237], v[96:97], s[100:101] op_sel_hi:[1,0]
	v_exp_f32_e32 v234, v234
	v_exp_f32_e32 v235, v235
	v_exp_f32_e32 v236, v236
	v_exp_f32_e32 v237, v237
	v_pk_add_f32 v[234:235], v[234:235], 1.0 op_sel_hi:[1,0]
	v_pk_add_f32 v[236:237], v[236:237], 1.0 op_sel_hi:[1,0]
	v_rcp_f32_e32 v234, v234
	v_rcp_f32_e32 v235, v235
	v_rcp_f32_e32 v236, v236
	v_rcp_f32_e32 v237, v237
	v_pk_mul_f32 v[86:87], v[94:95], v[86:87]
	v_pk_mul_f32 v[88:89], v[96:97], v[88:89]
	v_pk_mul_f32 v[86:87], v[86:87], v[234:235]
	v_pk_mul_f32 v[88:89], v[88:89], v[236:237]
	v_cvt_pk_bf16_f32 v238, v86, v87
	v_cvt_pk_bf16_f32 v239, v88, v89
	v_pk_mul_f32 v[234:235], v[90:91], s[100:101] op_sel_hi:[1,0]
	v_pk_mul_f32 v[236:237], v[92:93], s[100:101] op_sel_hi:[1,0]
	v_exp_f32_e32 v234, v234
	v_exp_f32_e32 v235, v235
	v_exp_f32_e32 v236, v236
	v_exp_f32_e32 v237, v237
	v_pk_add_f32 v[234:235], v[234:235], 1.0 op_sel_hi:[1,0]
	v_pk_add_f32 v[236:237], v[236:237], 1.0 op_sel_hi:[1,0]
	v_rcp_f32_e32 v234, v234
	v_rcp_f32_e32 v235, v235
	v_rcp_f32_e32 v236, v236
	v_rcp_f32_e32 v237, v237
	v_pk_mul_f32 v[82:83], v[90:91], v[82:83]
	v_pk_mul_f32 v[84:85], v[92:93], v[84:85]
	v_pk_mul_f32 v[82:83], v[82:83], v[234:235]
	v_pk_mul_f32 v[84:85], v[84:85], v[236:237]
	v_cvt_pk_bf16_f32 v240, v82, v83
	v_cvt_pk_bf16_f32 v241, v84, v85
	global_store_dwordx4 v[100:101], v[238:241], off
	s_nop 1
	v_div_scale_f32 v82, s[2:3], v182, v182, 1.0
	v_rcp_f32_e32 v84, v82
	v_add_u32_e32 v83, 0x80, v181
	v_fma_f32 v85, -v82, v84, 1.0
	v_fmac_f32_e32 v84, v85, v84
	v_div_scale_f32 v85, vcc, 1.0, v182, 1.0
	v_mul_f32_e32 v86, v85, v84
	v_fma_f32 v87, -v82, v86, v85
	v_fmac_f32_e32 v86, v87, v84
	v_fma_f32 v82, -v82, v86, v85
	v_div_fmas_f32 v82, v82, v84, v86
	v_div_fixup_f32 v82, v82, v182, 1.0
	ds_bpermute_b32 v84, v180, v82
	v_mad_i64_i32 v[86:87], s[2:3], v83, s59, v[162:163]
	v_lshl_add_u64 v[86:87], v[86:87], 0, v[164:165]
	s_andn2_b64 vcc, exec, s[38:39]
	s_waitcnt lgkmcnt(0)
	v_pk_fma_f32 v[62:63], v[62:63], v[84:85], v[78:79] op_sel_hi:[1,0,1]
	v_pk_fma_f32 v[64:65], v[64:65], v[84:85], v[80:81] op_sel_hi:[1,0,1]
	v_pk_fma_f32 v[54:55], v[54:55], v[84:85], v[70:71] op_sel_hi:[1,0,1]
	v_pk_fma_f32 v[56:57], v[56:57], v[84:85], v[72:73] op_sel_hi:[1,0,1]
	v_pk_fma_f32 v[58:59], v[58:59], v[84:85], v[74:75] op_sel_hi:[1,0,1]
	v_pk_fma_f32 v[60:61], v[60:61], v[84:85], v[76:77] op_sel_hi:[1,0,1]
	v_pk_fma_f32 v[50:51], v[50:51], v[84:85], v[66:67] op_sel_hi:[1,0,1]
	v_pk_fma_f32 v[52:53], v[52:53], v[84:85], v[68:69] op_sel_hi:[1,0,1]
	v_pk_mul_f32 v[234:235], v[62:63], s[100:101] op_sel_hi:[1,0]
	v_pk_mul_f32 v[236:237], v[64:65], s[100:101] op_sel_hi:[1,0]
	v_exp_f32_e32 v234, v234
	v_exp_f32_e32 v235, v235
	v_exp_f32_e32 v236, v236
	v_exp_f32_e32 v237, v237
	v_pk_add_f32 v[234:235], v[234:235], 1.0 op_sel_hi:[1,0]
	v_pk_add_f32 v[236:237], v[236:237], 1.0 op_sel_hi:[1,0]
	v_rcp_f32_e32 v234, v234
	v_rcp_f32_e32 v235, v235
	v_rcp_f32_e32 v236, v236
	v_rcp_f32_e32 v237, v237
	v_pk_mul_f32 v[54:55], v[62:63], v[54:55]
	v_pk_mul_f32 v[56:57], v[64:65], v[56:57]
	v_pk_mul_f32 v[54:55], v[54:55], v[234:235]
	v_pk_mul_f32 v[56:57], v[56:57], v[236:237]
	v_cvt_pk_bf16_f32 v238, v54, v55
	v_cvt_pk_bf16_f32 v239, v56, v57
	v_pk_mul_f32 v[234:235], v[58:59], s[100:101] op_sel_hi:[1,0]
	v_pk_mul_f32 v[236:237], v[60:61], s[100:101] op_sel_hi:[1,0]
	v_exp_f32_e32 v234, v234
	v_exp_f32_e32 v235, v235
	v_exp_f32_e32 v236, v236
	v_exp_f32_e32 v237, v237
	v_pk_add_f32 v[234:235], v[234:235], 1.0 op_sel_hi:[1,0]
	v_pk_add_f32 v[236:237], v[236:237], 1.0 op_sel_hi:[1,0]
	v_rcp_f32_e32 v234, v234
	v_rcp_f32_e32 v235, v235
	v_rcp_f32_e32 v236, v236
	v_rcp_f32_e32 v237, v237
	v_pk_mul_f32 v[50:51], v[58:59], v[50:51]
	v_pk_mul_f32 v[52:53], v[60:61], v[52:53]
	v_pk_mul_f32 v[50:51], v[50:51], v[234:235]
	v_pk_mul_f32 v[52:53], v[52:53], v[236:237]
	v_cvt_pk_bf16_f32 v240, v50, v51
	v_cvt_pk_bf16_f32 v241, v52, v53
	global_store_dwordx4 v[86:87], v[238:241], off
	ds_bpermute_b32 v50, v180, v82 offset:64
	v_add_u32_e32 v51, 0x90, v181
	v_mad_i64_i32 v[52:53], s[2:3], v51, s59, v[162:163]
	s_waitcnt lgkmcnt(0)
; __device__ __forceinline__ unsigned cvt_pk_bf16(float lo, float hi) { unsigned r; asm volatile("v_cvt_pk_bf16_f32 %0, %1, %2" : "=v"(r) : "v"(lo), "v"(hi)); return r; }
; __device__ __forceinline__ float silu_mul(float a, float b) { return a * b * __builtin_amdgcn_rcpf(1.0f + __builtin_amdgcn_exp2f(-a * LOG2E)); }
;     __device__ __forceinline__ void operator()(const f32x4 (&acc)[2][2][4][2], const Unit& u, int wr, int wc, int fr, int fq) const {
;     ...
;             for (int m = 0; m < 4; ++m) { const int row = row0 + ai * HALF + m * 16; const float rs = __shfl(ai ? rsl1 : rsl0, m * 16 + fr); bf16_t* rowp = O + (size_t)row * DFF + col0;
;                 const f32x4 a0 = acc[ai][0][m][0] * rs + ba0, a1 = acc[ai][0][m][1] * rs + ba1, b0 = acc[ai][1][m][0] * rs + bb0, b1 = acc[ai][1][m][1] * rs + bb1;
;                 u32x4 w; w.x = cvt_pk_bf16(silu_mul(a0[0], b0[0]), silu_mul(a0[1], b0[1])); w.y = cvt_pk_bf16(silu_mul(a0[2], b0[2]), silu_mul(a0[3], b0[3]));
;                 w.z = cvt_pk_bf16(silu_mul(a1[0], b1[0]), silu_mul(a1[1], b1[1])); w.w = cvt_pk_bf16(silu_mul(a1[2], b1[2]), silu_mul(a1[3], b1[3]));
;                 *(u32x4*)rowp = w; }
	v_lshl_add_u64 v[52:53], v[52:53], 0, v[164:165]
	v_pk_fma_f32 v[46:47], v[46:47], v[50:51], v[78:79] op_sel_hi:[1,0,1]
	v_pk_fma_f32 v[48:49], v[48:49], v[50:51], v[80:81] op_sel_hi:[1,0,1]
	v_pk_fma_f32 v[38:39], v[38:39], v[50:51], v[70:71] op_sel_hi:[1,0,1]
	v_pk_fma_f32 v[40:41], v[40:41], v[50:51], v[72:73] op_sel_hi:[1,0,1]
	v_pk_fma_f32 v[42:43], v[42:43], v[50:51], v[74:75] op_sel_hi:[1,0,1]
	v_pk_fma_f32 v[44:45], v[44:45], v[50:51], v[76:77] op_sel_hi:[1,0,1]
	v_pk_fma_f32 v[34:35], v[34:35], v[50:51], v[66:67] op_sel_hi:[1,0,1]
	v_pk_fma_f32 v[36:37], v[36:37], v[50:51], v[68:69] op_sel_hi:[1,0,1]
	v_pk_mul_f32 v[234:235], v[46:47], s[100:101] op_sel_hi:[1,0]
	v_pk_mul_f32 v[236:237], v[48:49], s[100:101] op_sel_hi:[1,0]
	v_exp_f32_e32 v234, v234
	v_exp_f32_e32 v235, v235
	v_exp_f32_e32 v236, v236
	v_exp_f32_e32 v237, v237
	v_pk_add_f32 v[234:235], v[234:235], 1.0 op_sel_hi:[1,0]
	v_pk_add_f32 v[236:237], v[236:237], 1.0 op_sel_hi:[1,0]
	v_rcp_f32_e32 v234, v234
	v_rcp_f32_e32 v235, v235
	v_rcp_f32_e32 v236, v236
	v_rcp_f32_e32 v237, v237
	v_pk_mul_f32 v[38:39], v[46:47], v[38:39]
	v_pk_mul_f32 v[40:41], v[48:49], v[40:41]
	v_pk_mul_f32 v[38:39], v[38:39], v[234:235]
	v_pk_mul_f32 v[40:41], v[40:41], v[236:237]
	v_cvt_pk_bf16_f32 v238, v38, v39
	v_cvt_pk_bf16_f32 v239, v40, v41
	v_pk_mul_f32 v[234:235], v[42:43], s[100:101] op_sel_hi:[1,0]
	v_pk_mul_f32 v[236:237], v[44:45], s[100:101] op_sel_hi:[1,0]
	v_exp_f32_e32 v234, v234
	v_exp_f32_e32 v235, v235
	v_exp_f32_e32 v236, v236
	v_exp_f32_e32 v237, v237
	v_pk_add_f32 v[234:235], v[234:235], 1.0 op_sel_hi:[1,0]
	v_pk_add_f32 v[236:237], v[236:237], 1.0 op_sel_hi:[1,0]
	v_rcp_f32_e32 v234, v234
	v_rcp_f32_e32 v235, v235
	v_rcp_f32_e32 v236, v236
	v_rcp_f32_e32 v237, v237
	v_pk_mul_f32 v[34:35], v[42:43], v[34:35]
	v_pk_mul_f32 v[36:37], v[44:45], v[36:37]
	v_pk_mul_f32 v[34:35], v[34:35], v[234:235]
	v_pk_mul_f32 v[36:37], v[36:37], v[236:237]
	v_cvt_pk_bf16_f32 v240, v34, v35
	v_cvt_pk_bf16_f32 v241, v36, v37
	global_store_dwordx4 v[52:53], v[238:241], off
	ds_bpermute_b32 v34, v180, v82 offset:128
	v_add_u32_e32 v35, 0xa0, v181
	v_mad_i64_i32 v[36:37], s[2:3], v35, s59, v[162:163]
	s_waitcnt lgkmcnt(0)
	v_lshl_add_u64 v[36:37], v[36:37], 0, v[164:165]
	v_pk_fma_f32 v[30:31], v[30:31], v[34:35], v[78:79] op_sel_hi:[1,0,1]
	v_pk_fma_f32 v[32:33], v[32:33], v[34:35], v[80:81] op_sel_hi:[1,0,1]
	v_pk_fma_f32 v[22:23], v[22:23], v[34:35], v[70:71] op_sel_hi:[1,0,1]
	v_pk_fma_f32 v[24:25], v[24:25], v[34:35], v[72:73] op_sel_hi:[1,0,1]
	v_pk_fma_f32 v[26:27], v[26:27], v[34:35], v[74:75] op_sel_hi:[1,0,1]
	v_pk_fma_f32 v[28:29], v[28:29], v[34:35], v[76:77] op_sel_hi:[1,0,1]
	v_pk_fma_f32 v[18:19], v[18:19], v[34:35], v[66:67] op_sel_hi:[1,0,1]
	v_pk_fma_f32 v[20:21], v[20:21], v[34:35], v[68:69] op_sel_hi:[1,0,1]
	v_pk_mul_f32 v[234:235], v[30:31], s[100:101] op_sel_hi:[1,0]
	v_pk_mul_f32 v[236:237], v[32:33], s[100:101] op_sel_hi:[1,0]
	v_exp_f32_e32 v234, v234
	v_exp_f32_e32 v235, v235
	v_exp_f32_e32 v236, v236
	v_exp_f32_e32 v237, v237
	v_pk_add_f32 v[234:235], v[234:235], 1.0 op_sel_hi:[1,0]
	v_pk_add_f32 v[236:237], v[236:237], 1.0 op_sel_hi:[1,0]
	v_rcp_f32_e32 v234, v234
	v_rcp_f32_e32 v235, v235
	v_rcp_f32_e32 v236, v236
	v_rcp_f32_e32 v237, v237
	v_pk_mul_f32 v[22:23], v[30:31], v[22:23]
	v_pk_mul_f32 v[24:25], v[32:33], v[24:25]
	v_pk_mul_f32 v[22:23], v[22:23], v[234:235]
	v_pk_mul_f32 v[24:25], v[24:25], v[236:237]
	v_cvt_pk_bf16_f32 v238, v22, v23
	v_cvt_pk_bf16_f32 v239, v24, v25
	v_pk_mul_f32 v[234:235], v[26:27], s[100:101] op_sel_hi:[1,0]
	v_pk_mul_f32 v[236:237], v[28:29], s[100:101] op_sel_hi:[1,0]
	v_exp_f32_e32 v234, v234
	v_exp_f32_e32 v235, v235
	v_exp_f32_e32 v236, v236
	v_exp_f32_e32 v237, v237
	v_pk_add_f32 v[234:235], v[234:235], 1.0 op_sel_hi:[1,0]
	v_pk_add_f32 v[236:237], v[236:237], 1.0 op_sel_hi:[1,0]
	v_rcp_f32_e32 v234, v234
	v_rcp_f32_e32 v235, v235
	v_rcp_f32_e32 v236, v236
	v_rcp_f32_e32 v237, v237
	v_pk_mul_f32 v[18:19], v[26:27], v[18:19]
	v_pk_mul_f32 v[20:21], v[28:29], v[20:21]
	v_pk_mul_f32 v[18:19], v[18:19], v[234:235]
	v_pk_mul_f32 v[20:21], v[20:21], v[236:237]
	v_cvt_pk_bf16_f32 v240, v18, v19
	v_cvt_pk_bf16_f32 v241, v20, v21
	global_store_dwordx4 v[36:37], v[238:241], off
	ds_bpermute_b32 v18, v180, v82 offset:192
	v_add_u32_e32 v19, 0xb0, v181
	v_mad_i64_i32 v[20:21], s[2:3], v19, s59, v[162:163]
	s_waitcnt lgkmcnt(0)
	v_lshl_add_u64 v[20:21], v[20:21], 0, v[164:165]
	s_mov_b64 s[2:3], -1
	v_pk_fma_f32 v[14:15], v[14:15], v[18:19], v[78:79] op_sel_hi:[1,0,1]
	v_pk_fma_f32 v[16:17], v[16:17], v[18:19], v[80:81] op_sel_hi:[1,0,1]
	v_pk_fma_f32 v[6:7], v[6:7], v[18:19], v[70:71] op_sel_hi:[1,0,1]
	v_pk_fma_f32 v[8:9], v[8:9], v[18:19], v[72:73] op_sel_hi:[1,0,1]
	v_pk_fma_f32 v[10:11], v[10:11], v[18:19], v[74:75] op_sel_hi:[1,0,1]
	v_pk_fma_f32 v[12:13], v[12:13], v[18:19], v[76:77] op_sel_hi:[1,0,1]
	v_pk_fma_f32 v[2:3], v[2:3], v[18:19], v[66:67] op_sel_hi:[1,0,1]
	v_pk_fma_f32 v[4:5], v[4:5], v[18:19], v[68:69] op_sel_hi:[1,0,1]
	v_pk_mul_f32 v[234:235], v[14:15], s[100:101] op_sel_hi:[1,0]
	v_pk_mul_f32 v[236:237], v[16:17], s[100:101] op_sel_hi:[1,0]
	v_exp_f32_e32 v234, v234
	v_exp_f32_e32 v235, v235
	v_exp_f32_e32 v236, v236
	v_exp_f32_e32 v237, v237
	v_pk_add_f32 v[234:235], v[234:235], 1.0 op_sel_hi:[1,0]
	v_pk_add_f32 v[236:237], v[236:237], 1.0 op_sel_hi:[1,0]
	v_rcp_f32_e32 v234, v234
	v_rcp_f32_e32 v235, v235
	v_rcp_f32_e32 v236, v236
	v_rcp_f32_e32 v237, v237
	v_pk_mul_f32 v[6:7], v[14:15], v[6:7]
	v_pk_mul_f32 v[8:9], v[16:17], v[8:9]
	v_pk_mul_f32 v[6:7], v[6:7], v[234:235]
	v_pk_mul_f32 v[8:9], v[8:9], v[236:237]
	v_cvt_pk_bf16_f32 v238, v6, v7
	v_cvt_pk_bf16_f32 v239, v8, v9
	v_pk_mul_f32 v[234:235], v[10:11], s[100:101] op_sel_hi:[1,0]
	v_pk_mul_f32 v[236:237], v[12:13], s[100:101] op_sel_hi:[1,0]
	v_exp_f32_e32 v234, v234
	v_exp_f32_e32 v235, v235
	v_exp_f32_e32 v236, v236
	v_exp_f32_e32 v237, v237
	v_pk_add_f32 v[234:235], v[234:235], 1.0 op_sel_hi:[1,0]
	v_pk_add_f32 v[236:237], v[236:237], 1.0 op_sel_hi:[1,0]
	v_rcp_f32_e32 v234, v234
	v_rcp_f32_e32 v235, v235
	v_rcp_f32_e32 v236, v236
	v_rcp_f32_e32 v237, v237
	v_pk_mul_f32 v[2:3], v[10:11], v[2:3]
	v_pk_mul_f32 v[4:5], v[12:13], v[4:5]
	v_pk_mul_f32 v[2:3], v[2:3], v[234:235]
	v_pk_mul_f32 v[4:5], v[4:5], v[236:237]
	v_cvt_pk_bf16_f32 v240, v2, v3
	v_cvt_pk_bf16_f32 v241, v4, v5
	global_store_dwordx4 v[20:21], v[238:241], off
	s_cbranch_vccnz .LBB0_184
	s_andn2_b64 vcc, exec, s[4:5]
	s_cbranch_vccnz .LBB0_183
	s_barrier
	s_branch .LBB0_183

; __device__ __forceinline__ unsigned cvt_pk_bf16(float lo, float hi) { unsigned r; asm volatile("v_cvt_pk_bf16_f32 %0, %1, %2" : "=v"(r) : "v"(lo), "v"(hi)); return r; }
; __device__ __forceinline__ float row_rstd(const float* ss, int row) { return 1.0f / sqrtf(ss[row] * (1.0f / DM) + 1e-6f); }
; __device__ __forceinline__ float silu_mul(float a, float b) { return a * b * __builtin_amdgcn_rcpf(1.0f + __builtin_amdgcn_exp2f(-a * LOG2E)); }
;     __device__ __forceinline__ void operator()(const f32x4 (&acc)[2][2][4][2], const Unit& u, int wr, int wc, int fr, int fq) const {
;         const int row0 = u.pm * BM + wr * 64 + fr, col0 = u.pn * HALF + wc * 32 + 8 * fq;
;         const int s = (u.pm < ML / BM) ? (u.pm >> 5) : 4;
;         const float* bp = bias + (size_t)s * BIAS_N + u.pn * BM + wc * 32 + 8 * fq;
;         const f32x4 ba0 = *(const f32x4*)bp, ba1 = *(const f32x4*)(bp + 4), bb0 = *(const f32x4*)(bp + HALF), bb1 = *(const f32x4*)(bp + HALF + 4);
;         const int lane = fq * 16 + fr;
;         const float rsl0 = row_rstd(ss, u.pm * BM + wr * 64 + lane), rsl1 = row_rstd(ss, u.pm * BM + HALF + wr * 64 + lane);
; #pragma unroll
;         for (int ai = 0; ai < 2; ++ai)
; #pragma unroll
;             for (int m = 0; m < 4; ++m) { const int row = row0 + ai * HALF + m * 16; const float rs = __shfl(ai ? rsl1 : rsl0, m * 16 + fr); bf16_t* rowp = O + (size_t)row * DFF + col0;
;                 const f32x4 a0 = acc[ai][0][m][0] * rs + ba0, a1 = acc[ai][0][m][1] * rs + ba1, b0 = acc[ai][1][m][0] * rs + bb0, b1 = acc[ai][1][m][1] * rs + bb1;
;                 u32x4 w; w.x = cvt_pk_bf16(silu_mul(a0[0], b0[0]), silu_mul(a0[1], b0[1])); w.y = cvt_pk_bf16(silu_mul(a0[2], b0[2]), silu_mul(a0[3], b0[3]));
;                 w.z = cvt_pk_bf16(silu_mul(a1[0], b1[0]), silu_mul(a1[1], b1[1])); w.w = cvt_pk_bf16(silu_mul(a1[2], b1[2]), silu_mul(a1[3], b1[3]));
;                 *(u32x4*)rowp = w; }
.LBB0_1470:
	s_lshl_b32 s2, s2, 8
	s_add_i32 s13, s2, s42
	s_lshl_b64 s[2:3], s[16:17], 2
	s_add_u32 s15, s43, s2
	s_addc_u32 s16, s44, s3
	s_lshl_b32 s2, s0, 8
	s_ashr_i32 s3, s2, 31
	s_lshl_b64 s[2:3], s[2:3], 2
	v_lshl_or_b32 v164, s0, 7, v173
	s_add_u32 s0, s15, s2
	s_addc_u32 s3, s16, s3
	v_or_b32_e32 v162, s13, v171
	s_add_u32 s2, s0, s50
	v_ashrrev_i32_e32 v163, 31, v162
	s_addc_u32 s3, s3, 0
	v_lshl_add_u64 v[162:163], v[162:163], 2, s[64:65]
	v_mov_b32_e32 v74, v234
	v_mov_b32_e32 v75, v235
	v_mov_b32_e32 v76, v236
	v_mov_b32_e32 v77, v237
	v_mov_b32_e32 v78, v238
	v_mov_b32_e32 v79, v239
	v_mov_b32_e32 v80, v240
	v_mov_b32_e32 v81, v241
	v_mov_b32_e32 v66, v242
	v_mov_b32_e32 v67, v243
	v_mov_b32_e32 v68, v244
	v_mov_b32_e32 v69, v245
	v_mov_b32_e32 v70, v246
	v_mov_b32_e32 v71, v247
	v_mov_b32_e32 v72, v248
	v_mov_b32_e32 v73, v249
	v_or_b32_e32 v181, s13, v169
	v_mov_b32_e32 v162, v250
	s_waitcnt vmcnt(0)
	v_fmamk_f32 v162, v162, 0x3a000000, v178
	v_cmp_gt_f32_e32 vcc, s51, v162
	v_mul_f32_e32 v163, 0x4f800000, v162
	s_nop 0
	v_cndmask_b32_e32 v162, v162, v163, vcc
	v_sqrt_f32_e32 v163, v162
	s_nop 0
	v_add_u32_e32 v165, -1, v163
	v_fma_f32 v166, -v165, v163, v162
	v_cmp_ge_f32_e64 s[2:3], 0, v166
	v_add_u32_e32 v166, 1, v163
	s_nop 0
	v_cndmask_b32_e64 v165, v163, v165, s[2:3]
	v_fma_f32 v163, -v166, v163, v162
	v_cmp_lt_f32_e64 s[2:3], 0, v163
	s_nop 1
	v_cndmask_b32_e64 v163, v165, v166, s[2:3]
	v_mul_f32_e32 v165, 0x37800000, v163
	v_cndmask_b32_e32 v163, v163, v165, vcc
	v_cmp_class_f32_e32 vcc, v162, v179
	s_nop 1
	v_cndmask_b32_e32 v166, v163, v162, vcc
	v_add_u32_e32 v162, s13, v172
	v_ashrrev_i32_e32 v163, 31, v162
	v_lshl_add_u64 v[162:163], v[162:163], 2, s[64:65]
	v_mov_b32_e32 v162, v251
	v_fmamk_f32 v162, v162, 0x3a000000, v178
	v_cmp_gt_f32_e32 vcc, s51, v162
	v_mul_f32_e32 v163, 0x4f800000, v162
	s_nop 0
	v_cndmask_b32_e32 v162, v162, v163, vcc
	v_sqrt_f32_e32 v163, v162
	s_nop 0
	v_add_u32_e32 v165, -1, v163
	v_fma_f32 v167, -v165, v163, v162
	v_cmp_ge_f32_e64 s[2:3], 0, v167
	v_add_u32_e32 v167, 1, v163
	s_nop 0
	v_cndmask_b32_e64 v165, v163, v165, s[2:3]
	v_fma_f32 v163, -v167, v163, v162
	v_cmp_lt_f32_e64 s[2:3], 0, v163
	s_nop 1
	v_cndmask_b32_e64 v163, v165, v167, s[2:3]
	v_mul_f32_e32 v165, 0x37800000, v163
	v_cndmask_b32_e32 v163, v163, v165, vcc
	v_cmp_class_f32_e32 vcc, v162, v179
	v_ashrrev_i32_e32 v165, 31, v164
	v_lshlrev_b64 v[164:165], 1, v[164:165]
	v_cndmask_b32_e32 v182, v163, v162, vcc
	v_div_scale_f32 v162, s[2:3], v166, v166, 1.0
	v_rcp_f32_e32 v163, v162
	s_nop 0
	v_fma_f32 v167, -v162, v163, 1.0
	v_fmac_f32_e32 v163, v167, v163
	v_div_scale_f32 v167, vcc, 1.0, v166, 1.0
	v_mul_f32_e32 v168, v167, v163
	v_fma_f32 v183, -v162, v168, v167
	v_fmac_f32_e32 v168, v183, v163
	v_fma_f32 v162, -v162, v168, v167
	v_div_fmas_f32 v162, v162, v163, v168
	v_div_fixup_f32 v183, v162, v166, 1.0
	s_mov_b32 s100, 0xbfb8aa3b
	ds_bpermute_b32 v168, v180, v183
	v_mov_b64_e32 v[162:163], s[96:97]
	v_mad_i64_i32 v[166:167], s[2:3], v181, s49, v[162:163]
	v_lshl_add_u64 v[166:167], v[166:167], 0, v[164:165]
	s_waitcnt lgkmcnt(0)
	v_pk_fma_f32 v[142:143], v[142:143], v[168:169], v[78:79] op_sel_hi:[1,0,1]
	v_pk_fma_f32 v[144:145], v[144:145], v[168:169], v[80:81] op_sel_hi:[1,0,1]
	v_pk_fma_f32 v[134:135], v[134:135], v[168:169], v[70:71] op_sel_hi:[1,0,1]
	v_pk_fma_f32 v[136:137], v[136:137], v[168:169], v[72:73] op_sel_hi:[1,0,1]
	v_pk_fma_f32 v[138:139], v[138:139], v[168:169], v[74:75] op_sel_hi:[1,0,1]
	v_pk_fma_f32 v[140:141], v[140:141], v[168:169], v[76:77] op_sel_hi:[1,0,1]
	v_pk_fma_f32 v[130:131], v[130:131], v[168:169], v[66:67] op_sel_hi:[1,0,1]
	v_pk_fma_f32 v[132:133], v[132:133], v[168:169], v[68:69] op_sel_hi:[1,0,1]
	v_pk_mul_f32 v[234:235], v[142:143], s[100:101] op_sel_hi:[1,0]
	v_pk_mul_f32 v[236:237], v[144:145], s[100:101] op_sel_hi:[1,0]
	v_exp_f32_e32 v234, v234
	v_exp_f32_e32 v235, v235
	v_exp_f32_e32 v236, v236
	v_exp_f32_e32 v237, v237
	v_pk_add_f32 v[234:235], v[234:235], 1.0 op_sel_hi:[1,0]
	v_pk_add_f32 v[236:237], v[236:237], 1.0 op_sel_hi:[1,0]
	v_rcp_f32_e32 v234, v234
	v_rcp_f32_e32 v235, v235
	v_rcp_f32_e32 v236, v236
	v_rcp_f32_e32 v237, v237
	v_pk_mul_f32 v[134:135], v[142:143], v[134:135]
	v_pk_mul_f32 v[136:137], v[144:145], v[136:137]
	v_pk_mul_f32 v[134:135], v[134:135], v[234:235]
	v_pk_mul_f32 v[136:137], v[136:137], v[236:237]
	v_cvt_pk_bf16_f32 v238, v134, v135
	v_cvt_pk_bf16_f32 v239, v136, v137
	v_pk_mul_f32 v[234:235], v[138:139], s[100:101] op_sel_hi:[1,0]
	v_pk_mul_f32 v[236:237], v[140:141], s[100:101] op_sel_hi:[1,0]
	v_exp_f32_e32 v234, v234
	v_exp_f32_e32 v235, v235
	v_exp_f32_e32 v236, v236
	v_exp_f32_e32 v237, v237
	v_pk_add_f32 v[234:235], v[234:235], 1.0 op_sel_hi:[1,0]
	v_pk_add_f32 v[236:237], v[236:237], 1.0 op_sel_hi:[1,0]
	v_rcp_f32_e32 v234, v234
	v_rcp_f32_e32 v235, v235
	v_rcp_f32_e32 v236, v236
	v_rcp_f32_e32 v237, v237
	v_pk_mul_f32 v[130:131], v[138:139], v[130:131]
	v_pk_mul_f32 v[132:133], v[140:141], v[132:133]
	v_pk_mul_f32 v[130:131], v[130:131], v[234:235]
	v_pk_mul_f32 v[132:133], v[132:133], v[236:237]
	v_cvt_pk_bf16_f32 v240, v130, v131
	v_cvt_pk_bf16_f32 v241, v132, v133
	global_store_dwordx4 v[166:167], v[238:241], off
	ds_bpermute_b32 v130, v180, v183 offset:64
	v_or_b32_e32 v131, 16, v181
	v_mad_i64_i32 v[132:133], s[2:3], v131, s49, v[162:163]
	s_waitcnt lgkmcnt(0)
; __device__ __forceinline__ unsigned cvt_pk_bf16(float lo, float hi) { unsigned r; asm volatile("v_cvt_pk_bf16_f32 %0, %1, %2" : "=v"(r) : "v"(lo), "v"(hi)); return r; }
; __device__ __forceinline__ float silu_mul(float a, float b) { return a * b * __builtin_amdgcn_rcpf(1.0f + __builtin_amdgcn_exp2f(-a * LOG2E)); }
;     __device__ __forceinline__ void operator()(const f32x4 (&acc)[2][2][4][2], const Unit& u, int wr, int wc, int fr, int fq) const {
;     ...
;             for (int m = 0; m < 4; ++m) { const int row = row0 + ai * HALF + m * 16; const float rs = __shfl(ai ? rsl1 : rsl0, m * 16 + fr); bf16_t* rowp = O + (size_t)row * DFF + col0;
;                 const f32x4 a0 = acc[ai][0][m][0] * rs + ba0, a1 = acc[ai][0][m][1] * rs + ba1, b0 = acc[ai][1][m][0] * rs + bb0, b1 = acc[ai][1][m][1] * rs + bb1;
;                 u32x4 w; w.x = cvt_pk_bf16(silu_mul(a0[0], b0[0]), silu_mul(a0[1], b0[1])); w.y = cvt_pk_bf16(silu_mul(a0[2], b0[2]), silu_mul(a0[3], b0[3]));
;                 w.z = cvt_pk_bf16(silu_mul(a1[0], b1[0]), silu_mul(a1[1], b1[1])); w.w = cvt_pk_bf16(silu_mul(a1[2], b1[2]), silu_mul(a1[3], b1[3]));
;                 *(u32x4*)rowp = w; }
	v_lshl_add_u64 v[132:133], v[132:133], 0, v[164:165]
	v_pk_fma_f32 v[126:127], v[126:127], v[130:131], v[78:79] op_sel_hi:[1,0,1]
	v_pk_fma_f32 v[128:129], v[128:129], v[130:131], v[80:81] op_sel_hi:[1,0,1]
	v_pk_fma_f32 v[118:119], v[118:119], v[130:131], v[70:71] op_sel_hi:[1,0,1]
	v_pk_fma_f32 v[120:121], v[120:121], v[130:131], v[72:73] op_sel_hi:[1,0,1]
	v_pk_fma_f32 v[122:123], v[122:123], v[130:131], v[74:75] op_sel_hi:[1,0,1]
	v_pk_fma_f32 v[124:125], v[124:125], v[130:131], v[76:77] op_sel_hi:[1,0,1]
	v_pk_fma_f32 v[114:115], v[114:115], v[130:131], v[66:67] op_sel_hi:[1,0,1]
	v_pk_fma_f32 v[116:117], v[116:117], v[130:131], v[68:69] op_sel_hi:[1,0,1]
	v_pk_mul_f32 v[234:235], v[126:127], s[100:101] op_sel_hi:[1,0]
	v_pk_mul_f32 v[236:237], v[128:129], s[100:101] op_sel_hi:[1,0]
	v_exp_f32_e32 v234, v234
	v_exp_f32_e32 v235, v235
	v_exp_f32_e32 v236, v236
	v_exp_f32_e32 v237, v237
	v_pk_add_f32 v[234:235], v[234:235], 1.0 op_sel_hi:[1,0]
	v_pk_add_f32 v[236:237], v[236:237], 1.0 op_sel_hi:[1,0]
	v_rcp_f32_e32 v234, v234
	v_rcp_f32_e32 v235, v235
	v_rcp_f32_e32 v236, v236
	v_rcp_f32_e32 v237, v237
	v_pk_mul_f32 v[118:119], v[126:127], v[118:119]
	v_pk_mul_f32 v[120:121], v[128:129], v[120:121]
	v_pk_mul_f32 v[118:119], v[118:119], v[234:235]
	v_pk_mul_f32 v[120:121], v[120:121], v[236:237]
	v_cvt_pk_bf16_f32 v238, v118, v119
	v_cvt_pk_bf16_f32 v239, v120, v121
	v_pk_mul_f32 v[234:235], v[122:123], s[100:101] op_sel_hi:[1,0]
	v_pk_mul_f32 v[236:237], v[124:125], s[100:101] op_sel_hi:[1,0]
	v_exp_f32_e32 v234, v234
	v_exp_f32_e32 v235, v235
	v_exp_f32_e32 v236, v236
	v_exp_f32_e32 v237, v237
	v_pk_add_f32 v[234:235], v[234:235], 1.0 op_sel_hi:[1,0]
	v_pk_add_f32 v[236:237], v[236:237], 1.0 op_sel_hi:[1,0]
	v_rcp_f32_e32 v234, v234
	v_rcp_f32_e32 v235, v235
	v_rcp_f32_e32 v236, v236
	v_rcp_f32_e32 v237, v237
	v_pk_mul_f32 v[114:115], v[122:123], v[114:115]
	v_pk_mul_f32 v[116:117], v[124:125], v[116:117]
	v_pk_mul_f32 v[114:115], v[114:115], v[234:235]
	v_pk_mul_f32 v[116:117], v[116:117], v[236:237]
	v_cvt_pk_bf16_f32 v240, v114, v115
	v_cvt_pk_bf16_f32 v241, v116, v117
	global_store_dwordx4 v[132:133], v[238:241], off
	ds_bpermute_b32 v114, v180, v183 offset:128
	v_or_b32_e32 v115, 32, v181
	v_mad_i64_i32 v[116:117], s[2:3], v115, s49, v[162:163]
	s_waitcnt lgkmcnt(0)
	v_lshl_add_u64 v[116:117], v[116:117], 0, v[164:165]
	v_pk_fma_f32 v[110:111], v[110:111], v[114:115], v[78:79] op_sel_hi:[1,0,1]
	v_pk_fma_f32 v[112:113], v[112:113], v[114:115], v[80:81] op_sel_hi:[1,0,1]
	v_pk_fma_f32 v[102:103], v[102:103], v[114:115], v[70:71] op_sel_hi:[1,0,1]
	v_pk_fma_f32 v[104:105], v[104:105], v[114:115], v[72:73] op_sel_hi:[1,0,1]
	v_pk_fma_f32 v[106:107], v[106:107], v[114:115], v[74:75] op_sel_hi:[1,0,1]
	v_pk_fma_f32 v[108:109], v[108:109], v[114:115], v[76:77] op_sel_hi:[1,0,1]
	v_pk_fma_f32 v[98:99], v[98:99], v[114:115], v[66:67] op_sel_hi:[1,0,1]
	v_pk_fma_f32 v[100:101], v[100:101], v[114:115], v[68:69] op_sel_hi:[1,0,1]
	v_pk_mul_f32 v[234:235], v[110:111], s[100:101] op_sel_hi:[1,0]
	v_pk_mul_f32 v[236:237], v[112:113], s[100:101] op_sel_hi:[1,0]
	v_exp_f32_e32 v234, v234
	v_exp_f32_e32 v235, v235
	v_exp_f32_e32 v236, v236
	v_exp_f32_e32 v237, v237
	v_pk_add_f32 v[234:235], v[234:235], 1.0 op_sel_hi:[1,0]
	v_pk_add_f32 v[236:237], v[236:237], 1.0 op_sel_hi:[1,0]
	v_rcp_f32_e32 v234, v234
	v_rcp_f32_e32 v235, v235
	v_rcp_f32_e32 v236, v236
	v_rcp_f32_e32 v237, v237
	v_pk_mul_f32 v[102:103], v[110:111], v[102:103]
	v_pk_mul_f32 v[104:105], v[112:113], v[104:105]
	v_pk_mul_f32 v[102:103], v[102:103], v[234:235]
	v_pk_mul_f32 v[104:105], v[104:105], v[236:237]
	v_cvt_pk_bf16_f32 v238, v102, v103
	v_cvt_pk_bf16_f32 v239, v104, v105
	v_pk_mul_f32 v[234:235], v[106:107], s[100:101] op_sel_hi:[1,0]
	v_pk_mul_f32 v[236:237], v[108:109], s[100:101] op_sel_hi:[1,0]
	v_exp_f32_e32 v234, v234
	v_exp_f32_e32 v235, v235
	v_exp_f32_e32 v236, v236
	v_exp_f32_e32 v237, v237
	v_pk_add_f32 v[234:235], v[234:235], 1.0 op_sel_hi:[1,0]
	v_pk_add_f32 v[236:237], v[236:237], 1.0 op_sel_hi:[1,0]
	v_rcp_f32_e32 v234, v234
	v_rcp_f32_e32 v235, v235
	v_rcp_f32_e32 v236, v236
	v_rcp_f32_e32 v237, v237
	v_pk_mul_f32 v[98:99], v[106:107], v[98:99]
	v_pk_mul_f32 v[100:101], v[108:109], v[100:101]
	v_pk_mul_f32 v[98:99], v[98:99], v[234:235]
	v_pk_mul_f32 v[100:101], v[100:101], v[236:237]
	v_cvt_pk_bf16_f32 v240, v98, v99
	v_cvt_pk_bf16_f32 v241, v100, v101
	global_store_dwordx4 v[116:117], v[238:241], off
	ds_bpermute_b32 v98, v180, v183 offset:192
	v_or_b32_e32 v99, 48, v181
	v_mad_i64_i32 v[100:101], s[2:3], v99, s49, v[162:163]
	s_waitcnt lgkmcnt(0)
; __device__ __forceinline__ unsigned cvt_pk_bf16(float lo, float hi) { unsigned r; asm volatile("v_cvt_pk_bf16_f32 %0, %1, %2" : "=v"(r) : "v"(lo), "v"(hi)); return r; }
; __device__ __forceinline__ float row_rstd(const float* ss, int row) { return 1.0f / sqrtf(ss[row] * (1.0f / DM) + 1e-6f); }
; __device__ __forceinline__ float silu_mul(float a, float b) { return a * b * __builtin_amdgcn_rcpf(1.0f + __builtin_amdgcn_exp2f(-a * LOG2E)); }
;     __device__ __forceinline__ void operator()(const f32x4 (&acc)[2][2][4][2], const Unit& u, int wr, int wc, int fr, int fq) const {
;     ...
;         const float rsl0 = row_rstd(ss, u.pm * BM + wr * 64 + lane), rsl1 = row_rstd(ss, u.pm * BM + HALF + wr * 64 + lane);
; #pragma unroll
;         for (int ai = 0; ai < 2; ++ai)
; #pragma unroll
;             for (int m = 0; m < 4; ++m) { const int row = row0 + ai * HALF + m * 16; const float rs = __shfl(ai ? rsl1 : rsl0, m * 16 + fr); bf16_t* rowp = O + (size_t)row * DFF + col0;
;                 const f32x4 a0 = acc[ai][0][m][0] * rs + ba0, a1 = acc[ai][0][m][1] * rs + ba1, b0 = acc[ai][1][m][0] * rs + bb0, b1 = acc[ai][1][m][1] * rs + bb1;
;                 u32x4 w; w.x = cvt_pk_bf16(silu_mul(a0[0], b0[0]), silu_mul(a0[1], b0[1])); w.y = cvt_pk_bf16(silu_mul(a0[2], b0[2]), silu_mul(a0[3], b0[3]));
;                 w.z = cvt_pk_bf16(silu_mul(a1[0], b1[0]), silu_mul(a1[1], b1[1])); w.w = cvt_pk_bf16(silu_mul(a1[2], b1[2]), silu_mul(a1[3], b1[3]));
;                 *(u32x4*)rowp = w; }
	v_lshl_add_u64 v[100:101], v[100:101], 0, v[164:165]
	v_pk_fma_f32 v[94:95], v[94:95], v[98:99], v[78:79] op_sel_hi:[1,0,1]
	v_pk_fma_f32 v[96:97], v[96:97], v[98:99], v[80:81] op_sel_hi:[1,0,1]
	v_pk_fma_f32 v[86:87], v[86:87], v[98:99], v[70:71] op_sel_hi:[1,0,1]
	v_pk_fma_f32 v[88:89], v[88:89], v[98:99], v[72:73] op_sel_hi:[1,0,1]
	v_pk_fma_f32 v[90:91], v[90:91], v[98:99], v[74:75] op_sel_hi:[1,0,1]
	v_pk_fma_f32 v[92:93], v[92:93], v[98:99], v[76:77] op_sel_hi:[1,0,1]
	v_pk_fma_f32 v[82:83], v[82:83], v[98:99], v[66:67] op_sel_hi:[1,0,1]
	v_pk_fma_f32 v[84:85], v[84:85], v[98:99], v[68:69] op_sel_hi:[1,0,1]
	v_pk_mul_f32 v[234:235], v[94:95], s[100:101] op_sel_hi:[1,0]
	v_pk_mul_f32 v[236:237], v[96:97], s[100:101] op_sel_hi:[1,0]
	v_exp_f32_e32 v234, v234
	v_exp_f32_e32 v235, v235
	v_exp_f32_e32 v236, v236
	v_exp_f32_e32 v237, v237
	v_pk_add_f32 v[234:235], v[234:235], 1.0 op_sel_hi:[1,0]
	v_pk_add_f32 v[236:237], v[236:237], 1.0 op_sel_hi:[1,0]
	v_rcp_f32_e32 v234, v234
	v_rcp_f32_e32 v235, v235
	v_rcp_f32_e32 v236, v236
	v_rcp_f32_e32 v237, v237
	v_pk_mul_f32 v[86:87], v[94:95], v[86:87]
	v_pk_mul_f32 v[88:89], v[96:97], v[88:89]
	v_pk_mul_f32 v[86:87], v[86:87], v[234:235]
	v_pk_mul_f32 v[88:89], v[88:89], v[236:237]
	v_cvt_pk_bf16_f32 v238, v86, v87
	v_cvt_pk_bf16_f32 v239, v88, v89
	v_pk_mul_f32 v[234:235], v[90:91], s[100:101] op_sel_hi:[1,0]
	v_pk_mul_f32 v[236:237], v[92:93], s[100:101] op_sel_hi:[1,0]
	v_exp_f32_e32 v234, v234
	v_exp_f32_e32 v235, v235
	v_exp_f32_e32 v236, v236
	v_exp_f32_e32 v237, v237
	v_pk_add_f32 v[234:235], v[234:235], 1.0 op_sel_hi:[1,0]
	v_pk_add_f32 v[236:237], v[236:237], 1.0 op_sel_hi:[1,0]
	v_rcp_f32_e32 v234, v234
	v_rcp_f32_e32 v235, v235
	v_rcp_f32_e32 v236, v236
	v_rcp_f32_e32 v237, v237
	v_pk_mul_f32 v[82:83], v[90:91], v[82:83]
	v_pk_mul_f32 v[84:85], v[92:93], v[84:85]
	v_pk_mul_f32 v[82:83], v[82:83], v[234:235]
	v_pk_mul_f32 v[84:85], v[84:85], v[236:237]
	v_cvt_pk_bf16_f32 v240, v82, v83
	v_cvt_pk_bf16_f32 v241, v84, v85
	global_store_dwordx4 v[100:101], v[238:241], off
	s_nop 1
	v_div_scale_f32 v82, s[2:3], v182, v182, 1.0
	v_rcp_f32_e32 v84, v82
	v_add_u32_e32 v83, 0x80, v181
	v_fma_f32 v85, -v82, v84, 1.0
	v_fmac_f32_e32 v84, v85, v84
	v_div_scale_f32 v85, vcc, 1.0, v182, 1.0
	v_mul_f32_e32 v86, v85, v84
	v_fma_f32 v87, -v82, v86, v85
	v_fmac_f32_e32 v86, v87, v84
	v_fma_f32 v82, -v82, v86, v85
	v_div_fmas_f32 v82, v82, v84, v86
	v_div_fixup_f32 v82, v82, v182, 1.0
	ds_bpermute_b32 v84, v180, v82
	v_mad_i64_i32 v[86:87], s[2:3], v83, s49, v[162:163]
	v_lshl_add_u64 v[86:87], v[86:87], 0, v[164:165]
	s_andn2_b64 vcc, exec, s[38:39]
	s_waitcnt lgkmcnt(0)
	v_pk_fma_f32 v[62:63], v[62:63], v[84:85], v[78:79] op_sel_hi:[1,0,1]
	v_pk_fma_f32 v[64:65], v[64:65], v[84:85], v[80:81] op_sel_hi:[1,0,1]
	v_pk_fma_f32 v[54:55], v[54:55], v[84:85], v[70:71] op_sel_hi:[1,0,1]
	v_pk_fma_f32 v[56:57], v[56:57], v[84:85], v[72:73] op_sel_hi:[1,0,1]
	v_pk_fma_f32 v[58:59], v[58:59], v[84:85], v[74:75] op_sel_hi:[1,0,1]
	v_pk_fma_f32 v[60:61], v[60:61], v[84:85], v[76:77] op_sel_hi:[1,0,1]
	v_pk_fma_f32 v[50:51], v[50:51], v[84:85], v[66:67] op_sel_hi:[1,0,1]
	v_pk_fma_f32 v[52:53], v[52:53], v[84:85], v[68:69] op_sel_hi:[1,0,1]
	v_pk_mul_f32 v[234:235], v[62:63], s[100:101] op_sel_hi:[1,0]
	v_pk_mul_f32 v[236:237], v[64:65], s[100:101] op_sel_hi:[1,0]
	v_exp_f32_e32 v234, v234
	v_exp_f32_e32 v235, v235
	v_exp_f32_e32 v236, v236
	v_exp_f32_e32 v237, v237
	v_pk_add_f32 v[234:235], v[234:235], 1.0 op_sel_hi:[1,0]
	v_pk_add_f32 v[236:237], v[236:237], 1.0 op_sel_hi:[1,0]
	v_rcp_f32_e32 v234, v234
	v_rcp_f32_e32 v235, v235
	v_rcp_f32_e32 v236, v236
	v_rcp_f32_e32 v237, v237
	v_pk_mul_f32 v[54:55], v[62:63], v[54:55]
	v_pk_mul_f32 v[56:57], v[64:65], v[56:57]
	v_pk_mul_f32 v[54:55], v[54:55], v[234:235]
	v_pk_mul_f32 v[56:57], v[56:57], v[236:237]
	v_cvt_pk_bf16_f32 v238, v54, v55
	v_cvt_pk_bf16_f32 v239, v56, v57
	v_pk_mul_f32 v[234:235], v[58:59], s[100:101] op_sel_hi:[1,0]
	v_pk_mul_f32 v[236:237], v[60:61], s[100:101] op_sel_hi:[1,0]
	v_exp_f32_e32 v234, v234
	v_exp_f32_e32 v235, v235
	v_exp_f32_e32 v236, v236
	v_exp_f32_e32 v237, v237
	v_pk_add_f32 v[234:235], v[234:235], 1.0 op_sel_hi:[1,0]
	v_pk_add_f32 v[236:237], v[236:237], 1.0 op_sel_hi:[1,0]
	v_rcp_f32_e32 v234, v234
	v_rcp_f32_e32 v235, v235
	v_rcp_f32_e32 v236, v236
	v_rcp_f32_e32 v237, v237
	v_pk_mul_f32 v[50:51], v[58:59], v[50:51]
	v_pk_mul_f32 v[52:53], v[60:61], v[52:53]
	v_pk_mul_f32 v[50:51], v[50:51], v[234:235]
	v_pk_mul_f32 v[52:53], v[52:53], v[236:237]
	v_cvt_pk_bf16_f32 v240, v50, v51
	v_cvt_pk_bf16_f32 v241, v52, v53
	global_store_dwordx4 v[86:87], v[238:241], off
	ds_bpermute_b32 v50, v180, v82 offset:64
	v_add_u32_e32 v51, 0x90, v181
	v_mad_i64_i32 v[52:53], s[2:3], v51, s49, v[162:163]
	s_waitcnt lgkmcnt(0)
; __device__ __forceinline__ unsigned cvt_pk_bf16(float lo, float hi) { unsigned r; asm volatile("v_cvt_pk_bf16_f32 %0, %1, %2" : "=v"(r) : "v"(lo), "v"(hi)); return r; }
; __device__ __forceinline__ float silu_mul(float a, float b) { return a * b * __builtin_amdgcn_rcpf(1.0f + __builtin_amdgcn_exp2f(-a * LOG2E)); }
;     __device__ __forceinline__ void operator()(const f32x4 (&acc)[2][2][4][2], const Unit& u, int wr, int wc, int fr, int fq) const {
;     ...
;             for (int m = 0; m < 4; ++m) { const int row = row0 + ai * HALF + m * 16; const float rs = __shfl(ai ? rsl1 : rsl0, m * 16 + fr); bf16_t* rowp = O + (size_t)row * DFF + col0;
;                 const f32x4 a0 = acc[ai][0][m][0] * rs + ba0, a1 = acc[ai][0][m][1] * rs + ba1, b0 = acc[ai][1][m][0] * rs + bb0, b1 = acc[ai][1][m][1] * rs + bb1;
;                 u32x4 w; w.x = cvt_pk_bf16(silu_mul(a0[0], b0[0]), silu_mul(a0[1], b0[1])); w.y = cvt_pk_bf16(silu_mul(a0[2], b0[2]), silu_mul(a0[3], b0[3]));
;                 w.z = cvt_pk_bf16(silu_mul(a1[0], b1[0]), silu_mul(a1[1], b1[1])); w.w = cvt_pk_bf16(silu_mul(a1[2], b1[2]), silu_mul(a1[3], b1[3]));
;                 *(u32x4*)rowp = w; }
	v_lshl_add_u64 v[52:53], v[52:53], 0, v[164:165]
	v_pk_fma_f32 v[46:47], v[46:47], v[50:51], v[78:79] op_sel_hi:[1,0,1]
	v_pk_fma_f32 v[48:49], v[48:49], v[50:51], v[80:81] op_sel_hi:[1,0,1]
	v_pk_fma_f32 v[38:39], v[38:39], v[50:51], v[70:71] op_sel_hi:[1,0,1]
	v_pk_fma_f32 v[40:41], v[40:41], v[50:51], v[72:73] op_sel_hi:[1,0,1]
	v_pk_fma_f32 v[42:43], v[42:43], v[50:51], v[74:75] op_sel_hi:[1,0,1]
	v_pk_fma_f32 v[44:45], v[44:45], v[50:51], v[76:77] op_sel_hi:[1,0,1]
	v_pk_fma_f32 v[34:35], v[34:35], v[50:51], v[66:67] op_sel_hi:[1,0,1]
	v_pk_fma_f32 v[36:37], v[36:37], v[50:51], v[68:69] op_sel_hi:[1,0,1]
	v_pk_mul_f32 v[234:235], v[46:47], s[100:101] op_sel_hi:[1,0]
	v_pk_mul_f32 v[236:237], v[48:49], s[100:101] op_sel_hi:[1,0]
	v_exp_f32_e32 v234, v234
	v_exp_f32_e32 v235, v235
	v_exp_f32_e32 v236, v236
	v_exp_f32_e32 v237, v237
	v_pk_add_f32 v[234:235], v[234:235], 1.0 op_sel_hi:[1,0]
	v_pk_add_f32 v[236:237], v[236:237], 1.0 op_sel_hi:[1,0]
	v_rcp_f32_e32 v234, v234
	v_rcp_f32_e32 v235, v235
	v_rcp_f32_e32 v236, v236
	v_rcp_f32_e32 v237, v237
	v_pk_mul_f32 v[38:39], v[46:47], v[38:39]
	v_pk_mul_f32 v[40:41], v[48:49], v[40:41]
	v_pk_mul_f32 v[38:39], v[38:39], v[234:235]
	v_pk_mul_f32 v[40:41], v[40:41], v[236:237]
	v_cvt_pk_bf16_f32 v238, v38, v39
	v_cvt_pk_bf16_f32 v239, v40, v41
	v_pk_mul_f32 v[234:235], v[42:43], s[100:101] op_sel_hi:[1,0]
	v_pk_mul_f32 v[236:237], v[44:45], s[100:101] op_sel_hi:[1,0]
	v_exp_f32_e32 v234, v234
	v_exp_f32_e32 v235, v235
	v_exp_f32_e32 v236, v236
	v_exp_f32_e32 v237, v237
	v_pk_add_f32 v[234:235], v[234:235], 1.0 op_sel_hi:[1,0]
	v_pk_add_f32 v[236:237], v[236:237], 1.0 op_sel_hi:[1,0]
	v_rcp_f32_e32 v234, v234
	v_rcp_f32_e32 v235, v235
	v_rcp_f32_e32 v236, v236
	v_rcp_f32_e32 v237, v237
	v_pk_mul_f32 v[34:35], v[42:43], v[34:35]
	v_pk_mul_f32 v[36:37], v[44:45], v[36:37]
	v_pk_mul_f32 v[34:35], v[34:35], v[234:235]
	v_pk_mul_f32 v[36:37], v[36:37], v[236:237]
	v_cvt_pk_bf16_f32 v240, v34, v35
	v_cvt_pk_bf16_f32 v241, v36, v37
	global_store_dwordx4 v[52:53], v[238:241], off
	ds_bpermute_b32 v34, v180, v82 offset:128
	v_add_u32_e32 v35, 0xa0, v181
	v_mad_i64_i32 v[36:37], s[2:3], v35, s49, v[162:163]
	s_waitcnt lgkmcnt(0)
	v_lshl_add_u64 v[36:37], v[36:37], 0, v[164:165]
	v_pk_fma_f32 v[30:31], v[30:31], v[34:35], v[78:79] op_sel_hi:[1,0,1]
	v_pk_fma_f32 v[32:33], v[32:33], v[34:35], v[80:81] op_sel_hi:[1,0,1]
	v_pk_fma_f32 v[22:23], v[22:23], v[34:35], v[70:71] op_sel_hi:[1,0,1]
	v_pk_fma_f32 v[24:25], v[24:25], v[34:35], v[72:73] op_sel_hi:[1,0,1]
	v_pk_fma_f32 v[26:27], v[26:27], v[34:35], v[74:75] op_sel_hi:[1,0,1]
	v_pk_fma_f32 v[28:29], v[28:29], v[34:35], v[76:77] op_sel_hi:[1,0,1]
	v_pk_fma_f32 v[18:19], v[18:19], v[34:35], v[66:67] op_sel_hi:[1,0,1]
	v_pk_fma_f32 v[20:21], v[20:21], v[34:35], v[68:69] op_sel_hi:[1,0,1]
	v_pk_mul_f32 v[234:235], v[30:31], s[100:101] op_sel_hi:[1,0]
	v_pk_mul_f32 v[236:237], v[32:33], s[100:101] op_sel_hi:[1,0]
	v_exp_f32_e32 v234, v234
	v_exp_f32_e32 v235, v235
	v_exp_f32_e32 v236, v236
	v_exp_f32_e32 v237, v237
	v_pk_add_f32 v[234:235], v[234:235], 1.0 op_sel_hi:[1,0]
	v_pk_add_f32 v[236:237], v[236:237], 1.0 op_sel_hi:[1,0]
	v_rcp_f32_e32 v234, v234
	v_rcp_f32_e32 v235, v235
	v_rcp_f32_e32 v236, v236
	v_rcp_f32_e32 v237, v237
	v_pk_mul_f32 v[22:23], v[30:31], v[22:23]
	v_pk_mul_f32 v[24:25], v[32:33], v[24:25]
	v_pk_mul_f32 v[22:23], v[22:23], v[234:235]
	v_pk_mul_f32 v[24:25], v[24:25], v[236:237]
	v_cvt_pk_bf16_f32 v238, v22, v23
	v_cvt_pk_bf16_f32 v239, v24, v25
	v_pk_mul_f32 v[234:235], v[26:27], s[100:101] op_sel_hi:[1,0]
	v_pk_mul_f32 v[236:237], v[28:29], s[100:101] op_sel_hi:[1,0]
	v_exp_f32_e32 v234, v234
	v_exp_f32_e32 v235, v235
	v_exp_f32_e32 v236, v236
	v_exp_f32_e32 v237, v237
	v_pk_add_f32 v[234:235], v[234:235], 1.0 op_sel_hi:[1,0]
	v_pk_add_f32 v[236:237], v[236:237], 1.0 op_sel_hi:[1,0]
	v_rcp_f32_e32 v234, v234
	v_rcp_f32_e32 v235, v235
	v_rcp_f32_e32 v236, v236
	v_rcp_f32_e32 v237, v237
	v_pk_mul_f32 v[18:19], v[26:27], v[18:19]
	v_pk_mul_f32 v[20:21], v[28:29], v[20:21]
	v_pk_mul_f32 v[18:19], v[18:19], v[234:235]
	v_pk_mul_f32 v[20:21], v[20:21], v[236:237]
	v_cvt_pk_bf16_f32 v240, v18, v19
	v_cvt_pk_bf16_f32 v241, v20, v21
	global_store_dwordx4 v[36:37], v[238:241], off
	ds_bpermute_b32 v18, v180, v82 offset:192
	v_add_u32_e32 v19, 0xb0, v181
	v_mad_i64_i32 v[20:21], s[2:3], v19, s49, v[162:163]
	s_waitcnt lgkmcnt(0)
	v_lshl_add_u64 v[20:21], v[20:21], 0, v[164:165]
	s_mov_b64 s[2:3], -1
	v_pk_fma_f32 v[14:15], v[14:15], v[18:19], v[78:79] op_sel_hi:[1,0,1]
	v_pk_fma_f32 v[16:17], v[16:17], v[18:19], v[80:81] op_sel_hi:[1,0,1]
	v_pk_fma_f32 v[6:7], v[6:7], v[18:19], v[70:71] op_sel_hi:[1,0,1]
	v_pk_fma_f32 v[8:9], v[8:9], v[18:19], v[72:73] op_sel_hi:[1,0,1]
	v_pk_fma_f32 v[10:11], v[10:11], v[18:19], v[74:75] op_sel_hi:[1,0,1]
	v_pk_fma_f32 v[12:13], v[12:13], v[18:19], v[76:77] op_sel_hi:[1,0,1]
	v_pk_fma_f32 v[2:3], v[2:3], v[18:19], v[66:67] op_sel_hi:[1,0,1]
	v_pk_fma_f32 v[4:5], v[4:5], v[18:19], v[68:69] op_sel_hi:[1,0,1]
	v_pk_mul_f32 v[234:235], v[14:15], s[100:101] op_sel_hi:[1,0]
	v_pk_mul_f32 v[236:237], v[16:17], s[100:101] op_sel_hi:[1,0]
	v_exp_f32_e32 v234, v234
	v_exp_f32_e32 v235, v235
	v_exp_f32_e32 v236, v236
	v_exp_f32_e32 v237, v237
	v_pk_add_f32 v[234:235], v[234:235], 1.0 op_sel_hi:[1,0]
	v_pk_add_f32 v[236:237], v[236:237], 1.0 op_sel_hi:[1,0]
	v_rcp_f32_e32 v234, v234
	v_rcp_f32_e32 v235, v235
	v_rcp_f32_e32 v236, v236
	v_rcp_f32_e32 v237, v237
	v_pk_mul_f32 v[6:7], v[14:15], v[6:7]
	v_pk_mul_f32 v[8:9], v[16:17], v[8:9]
	v_pk_mul_f32 v[6:7], v[6:7], v[234:235]
	v_pk_mul_f32 v[8:9], v[8:9], v[236:237]
	v_cvt_pk_bf16_f32 v238, v6, v7
	v_cvt_pk_bf16_f32 v239, v8, v9
	v_pk_mul_f32 v[234:235], v[10:11], s[100:101] op_sel_hi:[1,0]
	v_pk_mul_f32 v[236:237], v[12:13], s[100:101] op_sel_hi:[1,0]
	v_exp_f32_e32 v234, v234
	v_exp_f32_e32 v235, v235
	v_exp_f32_e32 v236, v236
	v_exp_f32_e32 v237, v237
	v_pk_add_f32 v[234:235], v[234:235], 1.0 op_sel_hi:[1,0]
	v_pk_add_f32 v[236:237], v[236:237], 1.0 op_sel_hi:[1,0]
	v_rcp_f32_e32 v234, v234
	v_rcp_f32_e32 v235, v235
	v_rcp_f32_e32 v236, v236
	v_rcp_f32_e32 v237, v237
	v_pk_mul_f32 v[2:3], v[10:11], v[2:3]
	v_pk_mul_f32 v[4:5], v[12:13], v[4:5]
	v_pk_mul_f32 v[2:3], v[2:3], v[234:235]
	v_pk_mul_f32 v[4:5], v[4:5], v[236:237]
	v_cvt_pk_bf16_f32 v240, v2, v3
	v_cvt_pk_bf16_f32 v241, v4, v5
	global_store_dwordx4 v[20:21], v[238:241], off
	s_cbranch_vccnz .LBB0_1461
	s_andn2_b64 vcc, exec, s[4:5]
	s_cbranch_vccnz .LBB0_1460
	s_barrier
	s_branch .LBB0_1460

; __device__ __forceinline__ unsigned cvt_pk_bf16(float lo, float hi) { unsigned r; asm volatile("v_cvt_pk_bf16_f32 %0, %1, %2" : "=v"(r) : "v"(lo), "v"(hi)); return r; }
; __device__ __forceinline__ float row_rstd(const float* ss, int row) { return 1.0f / sqrtf(ss[row] * (1.0f / DM) + 1e-6f); }
; __device__ __forceinline__ float silu_mul(float a, float b) { return a * b * __builtin_amdgcn_rcpf(1.0f + __builtin_amdgcn_exp2f(-a * LOG2E)); }
;     __device__ __forceinline__ void operator()(const f32x4 (&acc)[2][2][4][2], const Unit& u, int wr, int wc, int fr, int fq) const {
;         const int row0 = u.pm * BM + wr * 64 + fr, col0 = u.pn * HALF + wc * 32 + 8 * fq;
;         const int s = (u.pm < ML / BM) ? (u.pm >> 5) : 4;
;         const float* bp = bias + (size_t)s * BIAS_N + u.pn * BM + wc * 32 + 8 * fq;
;         const f32x4 ba0 = *(const f32x4*)bp, ba1 = *(const f32x4*)(bp + 4), bb0 = *(const f32x4*)(bp + HALF), bb1 = *(const f32x4*)(bp + HALF + 4);
;         const int lane = fq * 16 + fr;
;         const float rsl0 = row_rstd(ss, u.pm * BM + wr * 64 + lane), rsl1 = row_rstd(ss, u.pm * BM + HALF + wr * 64 + lane);
; #pragma unroll
;         for (int ai = 0; ai < 2; ++ai)
; #pragma unroll
;             for (int m = 0; m < 4; ++m) { const int row = row0 + ai * HALF + m * 16; const float rs = __shfl(ai ? rsl1 : rsl0, m * 16 + fr); bf16_t* rowp = O + (size_t)row * DFF + col0;
;                 const f32x4 a0 = acc[ai][0][m][0] * rs + ba0, a1 = acc[ai][0][m][1] * rs + ba1, b0 = acc[ai][1][m][0] * rs + bb0, b1 = acc[ai][1][m][1] * rs + bb1;
;                 u32x4 w; w.x = cvt_pk_bf16(silu_mul(a0[0], b0[0]), silu_mul(a0[1], b0[1])); w.y = cvt_pk_bf16(silu_mul(a0[2], b0[2]), silu_mul(a0[3], b0[3]));
;                 w.z = cvt_pk_bf16(silu_mul(a1[0], b1[0]), silu_mul(a1[1], b1[1])); w.w = cvt_pk_bf16(silu_mul(a1[2], b1[2]), silu_mul(a1[3], b1[3]));
;                 *(u32x4*)rowp = w; }
.LBB0_1827:
	s_lshl_b32 s2, s2, 8
	s_add_i32 s13, s2, s35
	s_lshl_b64 s[2:3], s[16:17], 2
	s_add_u32 s15, s36, s2
	s_addc_u32 s16, s37, s3
	s_lshl_b32 s2, s0, 8
	s_ashr_i32 s3, s2, 31
	s_lshl_b64 s[2:3], s[2:3], 2
	v_lshl_or_b32 v164, s0, 7, v172
	s_add_u32 s0, s15, s2
	s_addc_u32 s3, s16, s3
	v_or_b32_e32 v162, s13, v170
	s_add_u32 s2, s0, s47
	v_ashrrev_i32_e32 v163, 31, v162
	s_addc_u32 s3, s3, 0
	v_lshl_add_u64 v[162:163], v[162:163], 2, s[6:7]
	v_mov_b32_e32 v74, v234
	v_mov_b32_e32 v75, v235
	v_mov_b32_e32 v76, v236
	v_mov_b32_e32 v77, v237
	v_mov_b32_e32 v78, v238
	v_mov_b32_e32 v79, v239
	v_mov_b32_e32 v80, v240
	v_mov_b32_e32 v81, v241
	v_mov_b32_e32 v66, v242
	v_mov_b32_e32 v67, v243
	v_mov_b32_e32 v68, v244
	v_mov_b32_e32 v69, v245
	v_mov_b32_e32 v70, v246
	v_mov_b32_e32 v71, v247
	v_mov_b32_e32 v72, v248
	v_mov_b32_e32 v73, v249
	v_or_b32_e32 v180, s13, v1
	v_mov_b32_e32 v162, v250
	s_waitcnt vmcnt(0)
	v_fmamk_f32 v162, v162, 0x3a000000, v177
	v_cmp_gt_f32_e32 vcc, s48, v162
	v_mul_f32_e32 v163, 0x4f800000, v162
	s_nop 0
	v_cndmask_b32_e32 v162, v162, v163, vcc
	v_sqrt_f32_e32 v163, v162
	s_nop 0
	v_add_u32_e32 v165, -1, v163
	v_fma_f32 v166, -v165, v163, v162
	v_cmp_ge_f32_e64 s[2:3], 0, v166
	v_add_u32_e32 v166, 1, v163
	s_nop 0
	v_cndmask_b32_e64 v165, v163, v165, s[2:3]
	v_fma_f32 v163, -v166, v163, v162
	v_cmp_lt_f32_e64 s[2:3], 0, v163
	s_nop 1
	v_cndmask_b32_e64 v163, v165, v166, s[2:3]
	v_mul_f32_e32 v165, 0x37800000, v163
	v_cndmask_b32_e32 v163, v163, v165, vcc
	v_cmp_class_f32_e32 vcc, v162, v178
	s_nop 1
	v_cndmask_b32_e32 v166, v163, v162, vcc
	v_add_u32_e32 v162, s13, v171
	v_ashrrev_i32_e32 v163, 31, v162
	v_lshl_add_u64 v[162:163], v[162:163], 2, s[6:7]
	v_mov_b32_e32 v162, v251
	v_fmamk_f32 v162, v162, 0x3a000000, v177
	v_cmp_gt_f32_e32 vcc, s48, v162
	v_mul_f32_e32 v163, 0x4f800000, v162
	s_nop 0
	v_cndmask_b32_e32 v162, v162, v163, vcc
	v_sqrt_f32_e32 v163, v162
	s_nop 0
	v_add_u32_e32 v165, -1, v163
	v_fma_f32 v167, -v165, v163, v162
	v_cmp_ge_f32_e64 s[2:3], 0, v167
	v_add_u32_e32 v167, 1, v163
	s_nop 0
	v_cndmask_b32_e64 v165, v163, v165, s[2:3]
	v_fma_f32 v163, -v167, v163, v162
	v_cmp_lt_f32_e64 s[2:3], 0, v163
	s_nop 1
	v_cndmask_b32_e64 v163, v165, v167, s[2:3]
	v_mul_f32_e32 v165, 0x37800000, v163
	v_cndmask_b32_e32 v163, v163, v165, vcc
	v_cmp_class_f32_e32 vcc, v162, v178
	v_ashrrev_i32_e32 v165, 31, v164
	v_lshlrev_b64 v[164:165], 1, v[164:165]
	v_cndmask_b32_e32 v181, v163, v162, vcc
	v_div_scale_f32 v162, s[2:3], v166, v166, 1.0
	v_rcp_f32_e32 v163, v162
	s_nop 0
	v_fma_f32 v167, -v162, v163, 1.0
	v_fmac_f32_e32 v163, v167, v163
	v_div_scale_f32 v167, vcc, 1.0, v166, 1.0
	v_mul_f32_e32 v168, v167, v163
	v_fma_f32 v182, -v162, v168, v167
	v_fmac_f32_e32 v168, v182, v163
	v_fma_f32 v162, -v162, v168, v167
	v_div_fmas_f32 v162, v162, v163, v168
	v_div_fixup_f32 v182, v162, v166, 1.0
	s_mov_b32 s100, 0xbfb8aa3b
	ds_bpermute_b32 v168, v179, v182
	v_mov_b64_e32 v[162:163], s[96:97]
	v_mad_i64_i32 v[166:167], s[2:3], v180, s46, v[162:163]
	v_lshl_add_u64 v[166:167], v[166:167], 0, v[164:165]
	s_waitcnt lgkmcnt(0)
	v_pk_fma_f32 v[142:143], v[142:143], v[168:169], v[78:79] op_sel_hi:[1,0,1]
	v_pk_fma_f32 v[144:145], v[144:145], v[168:169], v[80:81] op_sel_hi:[1,0,1]
	v_pk_fma_f32 v[134:135], v[134:135], v[168:169], v[70:71] op_sel_hi:[1,0,1]
	v_pk_fma_f32 v[136:137], v[136:137], v[168:169], v[72:73] op_sel_hi:[1,0,1]
	v_pk_fma_f32 v[138:139], v[138:139], v[168:169], v[74:75] op_sel_hi:[1,0,1]
	v_pk_fma_f32 v[140:141], v[140:141], v[168:169], v[76:77] op_sel_hi:[1,0,1]
	v_pk_fma_f32 v[130:131], v[130:131], v[168:169], v[66:67] op_sel_hi:[1,0,1]
	v_pk_fma_f32 v[132:133], v[132:133], v[168:169], v[68:69] op_sel_hi:[1,0,1]
	v_pk_mul_f32 v[234:235], v[142:143], s[100:101] op_sel_hi:[1,0]
	v_pk_mul_f32 v[236:237], v[144:145], s[100:101] op_sel_hi:[1,0]
	v_exp_f32_e32 v234, v234
	v_exp_f32_e32 v235, v235
	v_exp_f32_e32 v236, v236
	v_exp_f32_e32 v237, v237
	v_pk_add_f32 v[234:235], v[234:235], 1.0 op_sel_hi:[1,0]
	v_pk_add_f32 v[236:237], v[236:237], 1.0 op_sel_hi:[1,0]
	v_rcp_f32_e32 v234, v234
	v_rcp_f32_e32 v235, v235
	v_rcp_f32_e32 v236, v236
	v_rcp_f32_e32 v237, v237
	v_pk_mul_f32 v[134:135], v[142:143], v[134:135]
	v_pk_mul_f32 v[136:137], v[144:145], v[136:137]
	v_pk_mul_f32 v[134:135], v[134:135], v[234:235]
	v_pk_mul_f32 v[136:137], v[136:137], v[236:237]
	v_cvt_pk_bf16_f32 v238, v134, v135
	v_cvt_pk_bf16_f32 v239, v136, v137
	v_pk_mul_f32 v[234:235], v[138:139], s[100:101] op_sel_hi:[1,0]
	v_pk_mul_f32 v[236:237], v[140:141], s[100:101] op_sel_hi:[1,0]
	v_exp_f32_e32 v234, v234
	v_exp_f32_e32 v235, v235
	v_exp_f32_e32 v236, v236
	v_exp_f32_e32 v237, v237
	v_pk_add_f32 v[234:235], v[234:235], 1.0 op_sel_hi:[1,0]
	v_pk_add_f32 v[236:237], v[236:237], 1.0 op_sel_hi:[1,0]
	v_rcp_f32_e32 v234, v234
	v_rcp_f32_e32 v235, v235
	v_rcp_f32_e32 v236, v236
	v_rcp_f32_e32 v237, v237
	v_pk_mul_f32 v[130:131], v[138:139], v[130:131]
	v_pk_mul_f32 v[132:133], v[140:141], v[132:133]
	v_pk_mul_f32 v[130:131], v[130:131], v[234:235]
	v_pk_mul_f32 v[132:133], v[132:133], v[236:237]
	v_cvt_pk_bf16_f32 v240, v130, v131
	v_cvt_pk_bf16_f32 v241, v132, v133
	global_store_dwordx4 v[166:167], v[238:241], off
	ds_bpermute_b32 v130, v179, v182 offset:64
	v_or_b32_e32 v131, 16, v180
	v_mad_i64_i32 v[132:133], s[2:3], v131, s46, v[162:163]
	s_waitcnt lgkmcnt(0)
; __device__ __forceinline__ unsigned cvt_pk_bf16(float lo, float hi) { unsigned r; asm volatile("v_cvt_pk_bf16_f32 %0, %1, %2" : "=v"(r) : "v"(lo), "v"(hi)); return r; }
; __device__ __forceinline__ float silu_mul(float a, float b) { return a * b * __builtin_amdgcn_rcpf(1.0f + __builtin_amdgcn_exp2f(-a * LOG2E)); }
;     __device__ __forceinline__ void operator()(const f32x4 (&acc)[2][2][4][2], const Unit& u, int wr, int wc, int fr, int fq) const {
;     ...
;             for (int m = 0; m < 4; ++m) { const int row = row0 + ai * HALF + m * 16; const float rs = __shfl(ai ? rsl1 : rsl0, m * 16 + fr); bf16_t* rowp = O + (size_t)row * DFF + col0;
;                 const f32x4 a0 = acc[ai][0][m][0] * rs + ba0, a1 = acc[ai][0][m][1] * rs + ba1, b0 = acc[ai][1][m][0] * rs + bb0, b1 = acc[ai][1][m][1] * rs + bb1;
;                 u32x4 w; w.x = cvt_pk_bf16(silu_mul(a0[0], b0[0]), silu_mul(a0[1], b0[1])); w.y = cvt_pk_bf16(silu_mul(a0[2], b0[2]), silu_mul(a0[3], b0[3]));
;                 w.z = cvt_pk_bf16(silu_mul(a1[0], b1[0]), silu_mul(a1[1], b1[1])); w.w = cvt_pk_bf16(silu_mul(a1[2], b1[2]), silu_mul(a1[3], b1[3]));
;                 *(u32x4*)rowp = w; }
	v_lshl_add_u64 v[132:133], v[132:133], 0, v[164:165]
	v_pk_fma_f32 v[126:127], v[126:127], v[130:131], v[78:79] op_sel_hi:[1,0,1]
	v_pk_fma_f32 v[128:129], v[128:129], v[130:131], v[80:81] op_sel_hi:[1,0,1]
	v_pk_fma_f32 v[118:119], v[118:119], v[130:131], v[70:71] op_sel_hi:[1,0,1]
	v_pk_fma_f32 v[120:121], v[120:121], v[130:131], v[72:73] op_sel_hi:[1,0,1]
	v_pk_fma_f32 v[122:123], v[122:123], v[130:131], v[74:75] op_sel_hi:[1,0,1]
	v_pk_fma_f32 v[124:125], v[124:125], v[130:131], v[76:77] op_sel_hi:[1,0,1]
	v_pk_fma_f32 v[114:115], v[114:115], v[130:131], v[66:67] op_sel_hi:[1,0,1]
	v_pk_fma_f32 v[116:117], v[116:117], v[130:131], v[68:69] op_sel_hi:[1,0,1]
	v_pk_mul_f32 v[234:235], v[126:127], s[100:101] op_sel_hi:[1,0]
	v_pk_mul_f32 v[236:237], v[128:129], s[100:101] op_sel_hi:[1,0]
	v_exp_f32_e32 v234, v234
	v_exp_f32_e32 v235, v235
	v_exp_f32_e32 v236, v236
	v_exp_f32_e32 v237, v237
	v_pk_add_f32 v[234:235], v[234:235], 1.0 op_sel_hi:[1,0]
	v_pk_add_f32 v[236:237], v[236:237], 1.0 op_sel_hi:[1,0]
	v_rcp_f32_e32 v234, v234
	v_rcp_f32_e32 v235, v235
	v_rcp_f32_e32 v236, v236
	v_rcp_f32_e32 v237, v237
	v_pk_mul_f32 v[118:119], v[126:127], v[118:119]
	v_pk_mul_f32 v[120:121], v[128:129], v[120:121]
	v_pk_mul_f32 v[118:119], v[118:119], v[234:235]
	v_pk_mul_f32 v[120:121], v[120:121], v[236:237]
	v_cvt_pk_bf16_f32 v238, v118, v119
	v_cvt_pk_bf16_f32 v239, v120, v121
	v_pk_mul_f32 v[234:235], v[122:123], s[100:101] op_sel_hi:[1,0]
	v_pk_mul_f32 v[236:237], v[124:125], s[100:101] op_sel_hi:[1,0]
	v_exp_f32_e32 v234, v234
	v_exp_f32_e32 v235, v235
	v_exp_f32_e32 v236, v236
	v_exp_f32_e32 v237, v237
	v_pk_add_f32 v[234:235], v[234:235], 1.0 op_sel_hi:[1,0]
	v_pk_add_f32 v[236:237], v[236:237], 1.0 op_sel_hi:[1,0]
	v_rcp_f32_e32 v234, v234
	v_rcp_f32_e32 v235, v235
	v_rcp_f32_e32 v236, v236
	v_rcp_f32_e32 v237, v237
	v_pk_mul_f32 v[114:115], v[122:123], v[114:115]
	v_pk_mul_f32 v[116:117], v[124:125], v[116:117]
	v_pk_mul_f32 v[114:115], v[114:115], v[234:235]
	v_pk_mul_f32 v[116:117], v[116:117], v[236:237]
	v_cvt_pk_bf16_f32 v240, v114, v115
	v_cvt_pk_bf16_f32 v241, v116, v117
	global_store_dwordx4 v[132:133], v[238:241], off
	ds_bpermute_b32 v114, v179, v182 offset:128
	v_or_b32_e32 v115, 32, v180
	v_mad_i64_i32 v[116:117], s[2:3], v115, s46, v[162:163]
	s_waitcnt lgkmcnt(0)
	v_lshl_add_u64 v[116:117], v[116:117], 0, v[164:165]
	v_pk_fma_f32 v[110:111], v[110:111], v[114:115], v[78:79] op_sel_hi:[1,0,1]
	v_pk_fma_f32 v[112:113], v[112:113], v[114:115], v[80:81] op_sel_hi:[1,0,1]
	v_pk_fma_f32 v[102:103], v[102:103], v[114:115], v[70:71] op_sel_hi:[1,0,1]
	v_pk_fma_f32 v[104:105], v[104:105], v[114:115], v[72:73] op_sel_hi:[1,0,1]
	v_pk_fma_f32 v[106:107], v[106:107], v[114:115], v[74:75] op_sel_hi:[1,0,1]
	v_pk_fma_f32 v[108:109], v[108:109], v[114:115], v[76:77] op_sel_hi:[1,0,1]
	v_pk_fma_f32 v[98:99], v[98:99], v[114:115], v[66:67] op_sel_hi:[1,0,1]
	v_pk_fma_f32 v[100:101], v[100:101], v[114:115], v[68:69] op_sel_hi:[1,0,1]
	v_pk_mul_f32 v[234:235], v[110:111], s[100:101] op_sel_hi:[1,0]
	v_pk_mul_f32 v[236:237], v[112:113], s[100:101] op_sel_hi:[1,0]
	v_exp_f32_e32 v234, v234
	v_exp_f32_e32 v235, v235
	v_exp_f32_e32 v236, v236
	v_exp_f32_e32 v237, v237
	v_pk_add_f32 v[234:235], v[234:235], 1.0 op_sel_hi:[1,0]
	v_pk_add_f32 v[236:237], v[236:237], 1.0 op_sel_hi:[1,0]
	v_rcp_f32_e32 v234, v234
	v_rcp_f32_e32 v235, v235
	v_rcp_f32_e32 v236, v236
	v_rcp_f32_e32 v237, v237
	v_pk_mul_f32 v[102:103], v[110:111], v[102:103]
	v_pk_mul_f32 v[104:105], v[112:113], v[104:105]
	v_pk_mul_f32 v[102:103], v[102:103], v[234:235]
	v_pk_mul_f32 v[104:105], v[104:105], v[236:237]
	v_cvt_pk_bf16_f32 v238, v102, v103
	v_cvt_pk_bf16_f32 v239, v104, v105
	v_pk_mul_f32 v[234:235], v[106:107], s[100:101] op_sel_hi:[1,0]
	v_pk_mul_f32 v[236:237], v[108:109], s[100:101] op_sel_hi:[1,0]
	v_exp_f32_e32 v234, v234
	v_exp_f32_e32 v235, v235
	v_exp_f32_e32 v236, v236
	v_exp_f32_e32 v237, v237
	v_pk_add_f32 v[234:235], v[234:235], 1.0 op_sel_hi:[1,0]
	v_pk_add_f32 v[236:237], v[236:237], 1.0 op_sel_hi:[1,0]
	v_rcp_f32_e32 v234, v234
	v_rcp_f32_e32 v235, v235
	v_rcp_f32_e32 v236, v236
	v_rcp_f32_e32 v237, v237
	v_pk_mul_f32 v[98:99], v[106:107], v[98:99]
	v_pk_mul_f32 v[100:101], v[108:109], v[100:101]
	v_pk_mul_f32 v[98:99], v[98:99], v[234:235]
	v_pk_mul_f32 v[100:101], v[100:101], v[236:237]
	v_cvt_pk_bf16_f32 v240, v98, v99
	v_cvt_pk_bf16_f32 v241, v100, v101
	global_store_dwordx4 v[116:117], v[238:241], off
	ds_bpermute_b32 v98, v179, v182 offset:192
	v_or_b32_e32 v99, 48, v180
	v_mad_i64_i32 v[100:101], s[2:3], v99, s46, v[162:163]
	s_waitcnt lgkmcnt(0)
; __device__ __forceinline__ unsigned cvt_pk_bf16(float lo, float hi) { unsigned r; asm volatile("v_cvt_pk_bf16_f32 %0, %1, %2" : "=v"(r) : "v"(lo), "v"(hi)); return r; }
; __device__ __forceinline__ float row_rstd(const float* ss, int row) { return 1.0f / sqrtf(ss[row] * (1.0f / DM) + 1e-6f); }
; __device__ __forceinline__ float silu_mul(float a, float b) { return a * b * __builtin_amdgcn_rcpf(1.0f + __builtin_amdgcn_exp2f(-a * LOG2E)); }
;     __device__ __forceinline__ void operator()(const f32x4 (&acc)[2][2][4][2], const Unit& u, int wr, int wc, int fr, int fq) const {
;     ...
;         const float rsl0 = row_rstd(ss, u.pm * BM + wr * 64 + lane), rsl1 = row_rstd(ss, u.pm * BM + HALF + wr * 64 + lane);
; #pragma unroll
;         for (int ai = 0; ai < 2; ++ai)
; #pragma unroll
;             for (int m = 0; m < 4; ++m) { const int row = row0 + ai * HALF + m * 16; const float rs = __shfl(ai ? rsl1 : rsl0, m * 16 + fr); bf16_t* rowp = O + (size_t)row * DFF + col0;
;                 const f32x4 a0 = acc[ai][0][m][0] * rs + ba0, a1 = acc[ai][0][m][1] * rs + ba1, b0 = acc[ai][1][m][0] * rs + bb0, b1 = acc[ai][1][m][1] * rs + bb1;
;                 u32x4 w; w.x = cvt_pk_bf16(silu_mul(a0[0], b0[0]), silu_mul(a0[1], b0[1])); w.y = cvt_pk_bf16(silu_mul(a0[2], b0[2]), silu_mul(a0[3], b0[3]));
;                 w.z = cvt_pk_bf16(silu_mul(a1[0], b1[0]), silu_mul(a1[1], b1[1])); w.w = cvt_pk_bf16(silu_mul(a1[2], b1[2]), silu_mul(a1[3], b1[3]));
;                 *(u32x4*)rowp = w; }
	v_lshl_add_u64 v[100:101], v[100:101], 0, v[164:165]
	v_pk_fma_f32 v[94:95], v[94:95], v[98:99], v[78:79] op_sel_hi:[1,0,1]
	v_pk_fma_f32 v[96:97], v[96:97], v[98:99], v[80:81] op_sel_hi:[1,0,1]
	v_pk_fma_f32 v[86:87], v[86:87], v[98:99], v[70:71] op_sel_hi:[1,0,1]
	v_pk_fma_f32 v[88:89], v[88:89], v[98:99], v[72:73] op_sel_hi:[1,0,1]
	v_pk_fma_f32 v[90:91], v[90:91], v[98:99], v[74:75] op_sel_hi:[1,0,1]
	v_pk_fma_f32 v[92:93], v[92:93], v[98:99], v[76:77] op_sel_hi:[1,0,1]
	v_pk_fma_f32 v[82:83], v[82:83], v[98:99], v[66:67] op_sel_hi:[1,0,1]
	v_pk_fma_f32 v[84:85], v[84:85], v[98:99], v[68:69] op_sel_hi:[1,0,1]
	v_pk_mul_f32 v[234:235], v[94:95], s[100:101] op_sel_hi:[1,0]
	v_pk_mul_f32 v[236:237], v[96:97], s[100:101] op_sel_hi:[1,0]
	v_exp_f32_e32 v234, v234
	v_exp_f32_e32 v235, v235
	v_exp_f32_e32 v236, v236
	v_exp_f32_e32 v237, v237
	v_pk_add_f32 v[234:235], v[234:235], 1.0 op_sel_hi:[1,0]
	v_pk_add_f32 v[236:237], v[236:237], 1.0 op_sel_hi:[1,0]
	v_rcp_f32_e32 v234, v234
	v_rcp_f32_e32 v235, v235
	v_rcp_f32_e32 v236, v236
	v_rcp_f32_e32 v237, v237
	v_pk_mul_f32 v[86:87], v[94:95], v[86:87]
	v_pk_mul_f32 v[88:89], v[96:97], v[88:89]
	v_pk_mul_f32 v[86:87], v[86:87], v[234:235]
	v_pk_mul_f32 v[88:89], v[88:89], v[236:237]
	v_cvt_pk_bf16_f32 v238, v86, v87
	v_cvt_pk_bf16_f32 v239, v88, v89
	v_pk_mul_f32 v[234:235], v[90:91], s[100:101] op_sel_hi:[1,0]
	v_pk_mul_f32 v[236:237], v[92:93], s[100:101] op_sel_hi:[1,0]
	v_exp_f32_e32 v234, v234
	v_exp_f32_e32 v235, v235
	v_exp_f32_e32 v236, v236
	v_exp_f32_e32 v237, v237
	v_pk_add_f32 v[234:235], v[234:235], 1.0 op_sel_hi:[1,0]
	v_pk_add_f32 v[236:237], v[236:237], 1.0 op_sel_hi:[1,0]
	v_rcp_f32_e32 v234, v234
	v_rcp_f32_e32 v235, v235
	v_rcp_f32_e32 v236, v236
	v_rcp_f32_e32 v237, v237
	v_pk_mul_f32 v[82:83], v[90:91], v[82:83]
	v_pk_mul_f32 v[84:85], v[92:93], v[84:85]
	v_pk_mul_f32 v[82:83], v[82:83], v[234:235]
	v_pk_mul_f32 v[84:85], v[84:85], v[236:237]
	v_cvt_pk_bf16_f32 v240, v82, v83
	v_cvt_pk_bf16_f32 v241, v84, v85
	global_store_dwordx4 v[100:101], v[238:241], off
	s_nop 1
	v_div_scale_f32 v82, s[2:3], v181, v181, 1.0
	v_rcp_f32_e32 v84, v82
	v_add_u32_e32 v83, 0x80, v180
	v_fma_f32 v85, -v82, v84, 1.0
	v_fmac_f32_e32 v84, v85, v84
	v_div_scale_f32 v85, vcc, 1.0, v181, 1.0
	v_mul_f32_e32 v86, v85, v84
	v_fma_f32 v87, -v82, v86, v85
	v_fmac_f32_e32 v86, v87, v84
	v_fma_f32 v82, -v82, v86, v85
	v_div_fmas_f32 v82, v82, v84, v86
	v_div_fixup_f32 v82, v82, v181, 1.0
	ds_bpermute_b32 v84, v179, v82
	v_mad_i64_i32 v[86:87], s[2:3], v83, s46, v[162:163]
	v_lshl_add_u64 v[86:87], v[86:87], 0, v[164:165]
	s_and_b64 vcc, s[38:39], exec
	s_waitcnt lgkmcnt(0)
	v_pk_fma_f32 v[62:63], v[62:63], v[84:85], v[78:79] op_sel_hi:[1,0,1]
	v_pk_fma_f32 v[64:65], v[64:65], v[84:85], v[80:81] op_sel_hi:[1,0,1]
	v_pk_fma_f32 v[54:55], v[54:55], v[84:85], v[70:71] op_sel_hi:[1,0,1]
	v_pk_fma_f32 v[56:57], v[56:57], v[84:85], v[72:73] op_sel_hi:[1,0,1]
	v_pk_fma_f32 v[58:59], v[58:59], v[84:85], v[74:75] op_sel_hi:[1,0,1]
	v_pk_fma_f32 v[60:61], v[60:61], v[84:85], v[76:77] op_sel_hi:[1,0,1]
	v_pk_fma_f32 v[50:51], v[50:51], v[84:85], v[66:67] op_sel_hi:[1,0,1]
	v_pk_fma_f32 v[52:53], v[52:53], v[84:85], v[68:69] op_sel_hi:[1,0,1]
	v_pk_mul_f32 v[234:235], v[62:63], s[100:101] op_sel_hi:[1,0]
	v_pk_mul_f32 v[236:237], v[64:65], s[100:101] op_sel_hi:[1,0]
	v_exp_f32_e32 v234, v234
	v_exp_f32_e32 v235, v235
	v_exp_f32_e32 v236, v236
	v_exp_f32_e32 v237, v237
	v_pk_add_f32 v[234:235], v[234:235], 1.0 op_sel_hi:[1,0]
	v_pk_add_f32 v[236:237], v[236:237], 1.0 op_sel_hi:[1,0]
	v_rcp_f32_e32 v234, v234
	v_rcp_f32_e32 v235, v235
	v_rcp_f32_e32 v236, v236
	v_rcp_f32_e32 v237, v237
	v_pk_mul_f32 v[54:55], v[62:63], v[54:55]
	v_pk_mul_f32 v[56:57], v[64:65], v[56:57]
	v_pk_mul_f32 v[54:55], v[54:55], v[234:235]
	v_pk_mul_f32 v[56:57], v[56:57], v[236:237]
	v_cvt_pk_bf16_f32 v238, v54, v55
	v_cvt_pk_bf16_f32 v239, v56, v57
	v_pk_mul_f32 v[234:235], v[58:59], s[100:101] op_sel_hi:[1,0]
	v_pk_mul_f32 v[236:237], v[60:61], s[100:101] op_sel_hi:[1,0]
	v_exp_f32_e32 v234, v234
	v_exp_f32_e32 v235, v235
	v_exp_f32_e32 v236, v236
	v_exp_f32_e32 v237, v237
	v_pk_add_f32 v[234:235], v[234:235], 1.0 op_sel_hi:[1,0]
	v_pk_add_f32 v[236:237], v[236:237], 1.0 op_sel_hi:[1,0]
	v_rcp_f32_e32 v234, v234
	v_rcp_f32_e32 v235, v235
	v_rcp_f32_e32 v236, v236
	v_rcp_f32_e32 v237, v237
	v_pk_mul_f32 v[50:51], v[58:59], v[50:51]
	v_pk_mul_f32 v[52:53], v[60:61], v[52:53]
	v_pk_mul_f32 v[50:51], v[50:51], v[234:235]
	v_pk_mul_f32 v[52:53], v[52:53], v[236:237]
	v_cvt_pk_bf16_f32 v240, v50, v51
	v_cvt_pk_bf16_f32 v241, v52, v53
	global_store_dwordx4 v[86:87], v[238:241], off
	ds_bpermute_b32 v50, v179, v82 offset:64
	v_add_u32_e32 v51, 0x90, v180
	v_mad_i64_i32 v[52:53], s[2:3], v51, s46, v[162:163]
	s_waitcnt lgkmcnt(0)
; __device__ __forceinline__ unsigned cvt_pk_bf16(float lo, float hi) { unsigned r; asm volatile("v_cvt_pk_bf16_f32 %0, %1, %2" : "=v"(r) : "v"(lo), "v"(hi)); return r; }
; __device__ __forceinline__ float silu_mul(float a, float b) { return a * b * __builtin_amdgcn_rcpf(1.0f + __builtin_amdgcn_exp2f(-a * LOG2E)); }
;     __device__ __forceinline__ void operator()(const f32x4 (&acc)[2][2][4][2], const Unit& u, int wr, int wc, int fr, int fq) const {
;     ...
;             for (int m = 0; m < 4; ++m) { const int row = row0 + ai * HALF + m * 16; const float rs = __shfl(ai ? rsl1 : rsl0, m * 16 + fr); bf16_t* rowp = O + (size_t)row * DFF + col0;
;                 const f32x4 a0 = acc[ai][0][m][0] * rs + ba0, a1 = acc[ai][0][m][1] * rs + ba1, b0 = acc[ai][1][m][0] * rs + bb0, b1 = acc[ai][1][m][1] * rs + bb1;
;                 u32x4 w; w.x = cvt_pk_bf16(silu_mul(a0[0], b0[0]), silu_mul(a0[1], b0[1])); w.y = cvt_pk_bf16(silu_mul(a0[2], b0[2]), silu_mul(a0[3], b0[3]));
;                 w.z = cvt_pk_bf16(silu_mul(a1[0], b1[0]), silu_mul(a1[1], b1[1])); w.w = cvt_pk_bf16(silu_mul(a1[2], b1[2]), silu_mul(a1[3], b1[3]));
;                 *(u32x4*)rowp = w; }
	v_lshl_add_u64 v[52:53], v[52:53], 0, v[164:165]
	v_pk_fma_f32 v[46:47], v[46:47], v[50:51], v[78:79] op_sel_hi:[1,0,1]
	v_pk_fma_f32 v[48:49], v[48:49], v[50:51], v[80:81] op_sel_hi:[1,0,1]
	v_pk_fma_f32 v[38:39], v[38:39], v[50:51], v[70:71] op_sel_hi:[1,0,1]
	v_pk_fma_f32 v[40:41], v[40:41], v[50:51], v[72:73] op_sel_hi:[1,0,1]
	v_pk_fma_f32 v[42:43], v[42:43], v[50:51], v[74:75] op_sel_hi:[1,0,1]
	v_pk_fma_f32 v[44:45], v[44:45], v[50:51], v[76:77] op_sel_hi:[1,0,1]
	v_pk_fma_f32 v[34:35], v[34:35], v[50:51], v[66:67] op_sel_hi:[1,0,1]
	v_pk_fma_f32 v[36:37], v[36:37], v[50:51], v[68:69] op_sel_hi:[1,0,1]
	v_pk_mul_f32 v[234:235], v[46:47], s[100:101] op_sel_hi:[1,0]
	v_pk_mul_f32 v[236:237], v[48:49], s[100:101] op_sel_hi:[1,0]
	v_exp_f32_e32 v234, v234
	v_exp_f32_e32 v235, v235
	v_exp_f32_e32 v236, v236
	v_exp_f32_e32 v237, v237
	v_pk_add_f32 v[234:235], v[234:235], 1.0 op_sel_hi:[1,0]
	v_pk_add_f32 v[236:237], v[236:237], 1.0 op_sel_hi:[1,0]
	v_rcp_f32_e32 v234, v234
	v_rcp_f32_e32 v235, v235
	v_rcp_f32_e32 v236, v236
	v_rcp_f32_e32 v237, v237
	v_pk_mul_f32 v[38:39], v[46:47], v[38:39]
	v_pk_mul_f32 v[40:41], v[48:49], v[40:41]
	v_pk_mul_f32 v[38:39], v[38:39], v[234:235]
	v_pk_mul_f32 v[40:41], v[40:41], v[236:237]
	v_cvt_pk_bf16_f32 v238, v38, v39
	v_cvt_pk_bf16_f32 v239, v40, v41
	v_pk_mul_f32 v[234:235], v[42:43], s[100:101] op_sel_hi:[1,0]
	v_pk_mul_f32 v[236:237], v[44:45], s[100:101] op_sel_hi:[1,0]
	v_exp_f32_e32 v234, v234
	v_exp_f32_e32 v235, v235
	v_exp_f32_e32 v236, v236
	v_exp_f32_e32 v237, v237
	v_pk_add_f32 v[234:235], v[234:235], 1.0 op_sel_hi:[1,0]
	v_pk_add_f32 v[236:237], v[236:237], 1.0 op_sel_hi:[1,0]
	v_rcp_f32_e32 v234, v234
	v_rcp_f32_e32 v235, v235
	v_rcp_f32_e32 v236, v236
	v_rcp_f32_e32 v237, v237
	v_pk_mul_f32 v[34:35], v[42:43], v[34:35]
	v_pk_mul_f32 v[36:37], v[44:45], v[36:37]
	v_pk_mul_f32 v[34:35], v[34:35], v[234:235]
	v_pk_mul_f32 v[36:37], v[36:37], v[236:237]
	v_cvt_pk_bf16_f32 v240, v34, v35
	v_cvt_pk_bf16_f32 v241, v36, v37
	global_store_dwordx4 v[52:53], v[238:241], off
	ds_bpermute_b32 v34, v179, v82 offset:128
	v_add_u32_e32 v35, 0xa0, v180
	v_mad_i64_i32 v[36:37], s[2:3], v35, s46, v[162:163]
	s_waitcnt lgkmcnt(0)
	v_lshl_add_u64 v[36:37], v[36:37], 0, v[164:165]
	v_pk_fma_f32 v[30:31], v[30:31], v[34:35], v[78:79] op_sel_hi:[1,0,1]
	v_pk_fma_f32 v[32:33], v[32:33], v[34:35], v[80:81] op_sel_hi:[1,0,1]
	v_pk_fma_f32 v[22:23], v[22:23], v[34:35], v[70:71] op_sel_hi:[1,0,1]
	v_pk_fma_f32 v[24:25], v[24:25], v[34:35], v[72:73] op_sel_hi:[1,0,1]
	v_pk_fma_f32 v[26:27], v[26:27], v[34:35], v[74:75] op_sel_hi:[1,0,1]
	v_pk_fma_f32 v[28:29], v[28:29], v[34:35], v[76:77] op_sel_hi:[1,0,1]
	v_pk_fma_f32 v[18:19], v[18:19], v[34:35], v[66:67] op_sel_hi:[1,0,1]
	v_pk_fma_f32 v[20:21], v[20:21], v[34:35], v[68:69] op_sel_hi:[1,0,1]
	v_pk_mul_f32 v[234:235], v[30:31], s[100:101] op_sel_hi:[1,0]
	v_pk_mul_f32 v[236:237], v[32:33], s[100:101] op_sel_hi:[1,0]
	v_exp_f32_e32 v234, v234
	v_exp_f32_e32 v235, v235
	v_exp_f32_e32 v236, v236
	v_exp_f32_e32 v237, v237
	v_pk_add_f32 v[234:235], v[234:235], 1.0 op_sel_hi:[1,0]
	v_pk_add_f32 v[236:237], v[236:237], 1.0 op_sel_hi:[1,0]
	v_rcp_f32_e32 v234, v234
	v_rcp_f32_e32 v235, v235
	v_rcp_f32_e32 v236, v236
	v_rcp_f32_e32 v237, v237
	v_pk_mul_f32 v[22:23], v[30:31], v[22:23]
	v_pk_mul_f32 v[24:25], v[32:33], v[24:25]
	v_pk_mul_f32 v[22:23], v[22:23], v[234:235]
	v_pk_mul_f32 v[24:25], v[24:25], v[236:237]
	v_cvt_pk_bf16_f32 v238, v22, v23
	v_cvt_pk_bf16_f32 v239, v24, v25
	v_pk_mul_f32 v[234:235], v[26:27], s[100:101] op_sel_hi:[1,0]
	v_pk_mul_f32 v[236:237], v[28:29], s[100:101] op_sel_hi:[1,0]
	v_exp_f32_e32 v234, v234
	v_exp_f32_e32 v235, v235
	v_exp_f32_e32 v236, v236
	v_exp_f32_e32 v237, v237
	v_pk_add_f32 v[234:235], v[234:235], 1.0 op_sel_hi:[1,0]
	v_pk_add_f32 v[236:237], v[236:237], 1.0 op_sel_hi:[1,0]
	v_rcp_f32_e32 v234, v234
	v_rcp_f32_e32 v235, v235
	v_rcp_f32_e32 v236, v236
	v_rcp_f32_e32 v237, v237
	v_pk_mul_f32 v[18:19], v[26:27], v[18:19]
	v_pk_mul_f32 v[20:21], v[28:29], v[20:21]
	v_pk_mul_f32 v[18:19], v[18:19], v[234:235]
	v_pk_mul_f32 v[20:21], v[20:21], v[236:237]
	v_cvt_pk_bf16_f32 v240, v18, v19
	v_cvt_pk_bf16_f32 v241, v20, v21
	global_store_dwordx4 v[36:37], v[238:241], off
	ds_bpermute_b32 v18, v179, v82 offset:192
	v_add_u32_e32 v19, 0xb0, v180
	v_mad_i64_i32 v[20:21], s[2:3], v19, s46, v[162:163]
	s_waitcnt lgkmcnt(0)
	v_lshl_add_u64 v[20:21], v[20:21], 0, v[164:165]
	s_mov_b64 s[2:3], -1
	v_pk_fma_f32 v[14:15], v[14:15], v[18:19], v[78:79] op_sel_hi:[1,0,1]
	v_pk_fma_f32 v[16:17], v[16:17], v[18:19], v[80:81] op_sel_hi:[1,0,1]
	v_pk_fma_f32 v[6:7], v[6:7], v[18:19], v[70:71] op_sel_hi:[1,0,1]
	v_pk_fma_f32 v[8:9], v[8:9], v[18:19], v[72:73] op_sel_hi:[1,0,1]
	v_pk_fma_f32 v[10:11], v[10:11], v[18:19], v[74:75] op_sel_hi:[1,0,1]
	v_pk_fma_f32 v[12:13], v[12:13], v[18:19], v[76:77] op_sel_hi:[1,0,1]
	v_pk_fma_f32 v[2:3], v[2:3], v[18:19], v[66:67] op_sel_hi:[1,0,1]
	v_pk_fma_f32 v[4:5], v[4:5], v[18:19], v[68:69] op_sel_hi:[1,0,1]
	v_pk_mul_f32 v[234:235], v[14:15], s[100:101] op_sel_hi:[1,0]
	v_pk_mul_f32 v[236:237], v[16:17], s[100:101] op_sel_hi:[1,0]
	v_exp_f32_e32 v234, v234
	v_exp_f32_e32 v235, v235
	v_exp_f32_e32 v236, v236
	v_exp_f32_e32 v237, v237
	v_pk_add_f32 v[234:235], v[234:235], 1.0 op_sel_hi:[1,0]
	v_pk_add_f32 v[236:237], v[236:237], 1.0 op_sel_hi:[1,0]
	v_rcp_f32_e32 v234, v234
	v_rcp_f32_e32 v235, v235
	v_rcp_f32_e32 v236, v236
	v_rcp_f32_e32 v237, v237
	v_pk_mul_f32 v[6:7], v[14:15], v[6:7]
	v_pk_mul_f32 v[8:9], v[16:17], v[8:9]
	v_pk_mul_f32 v[6:7], v[6:7], v[234:235]
	v_pk_mul_f32 v[8:9], v[8:9], v[236:237]
	v_cvt_pk_bf16_f32 v238, v6, v7
	v_cvt_pk_bf16_f32 v239, v8, v9
	v_pk_mul_f32 v[234:235], v[10:11], s[100:101] op_sel_hi:[1,0]
	v_pk_mul_f32 v[236:237], v[12:13], s[100:101] op_sel_hi:[1,0]
	v_exp_f32_e32 v234, v234
	v_exp_f32_e32 v235, v235
	v_exp_f32_e32 v236, v236
	v_exp_f32_e32 v237, v237
	v_pk_add_f32 v[234:235], v[234:235], 1.0 op_sel_hi:[1,0]
	v_pk_add_f32 v[236:237], v[236:237], 1.0 op_sel_hi:[1,0]
	v_rcp_f32_e32 v234, v234
	v_rcp_f32_e32 v235, v235
	v_rcp_f32_e32 v236, v236
	v_rcp_f32_e32 v237, v237
	v_pk_mul_f32 v[2:3], v[10:11], v[2:3]
	v_pk_mul_f32 v[4:5], v[12:13], v[4:5]
	v_pk_mul_f32 v[2:3], v[2:3], v[234:235]
	v_pk_mul_f32 v[4:5], v[4:5], v[236:237]
	v_cvt_pk_bf16_f32 v240, v2, v3
	v_cvt_pk_bf16_f32 v241, v4, v5
	global_store_dwordx4 v[20:21], v[238:241], off
	s_cbranch_vccz .LBB0_1818
	s_andn2_b64 vcc, exec, s[4:5]
	s_cbranch_vccnz .LBB0_1817
	s_barrier
	s_branch .LBB0_1817

; __device__ __forceinline__ unsigned cvt_pk_bf16(float lo, float hi) { unsigned r; asm volatile("v_cvt_pk_bf16_f32 %0, %1, %2" : "=v"(r) : "v"(lo), "v"(hi)); return r; }
; __device__ __forceinline__ float row_rstd(const float* ss, int row) { return 1.0f / sqrtf(ss[row] * (1.0f / DM) + 1e-6f); }
; __device__ __forceinline__ float silu_mul(float a, float b) { return a * b * __builtin_amdgcn_rcpf(1.0f + __builtin_amdgcn_exp2f(-a * LOG2E)); }
;     __device__ __forceinline__ void operator()(const f32x4 (&acc)[2][2][4][2], const Unit& u, int wr, int wc, int fr, int fq) const {
;         const int row0 = u.pm * BM + wr * 64 + fr, col0 = u.pn * HALF + wc * 32 + 8 * fq;
;         const int s = (u.pm < ML / BM) ? (u.pm >> 5) : 4;
;         const float* bp = bias + (size_t)s * BIAS_N + u.pn * BM + wc * 32 + 8 * fq;
;         const f32x4 ba0 = *(const f32x4*)bp, ba1 = *(const f32x4*)(bp + 4), bb0 = *(const f32x4*)(bp + HALF), bb1 = *(const f32x4*)(bp + HALF + 4);
;         const int lane = fq * 16 + fr;
;         const float rsl0 = row_rstd(ss, u.pm * BM + wr * 64 + lane), rsl1 = row_rstd(ss, u.pm * BM + HALF + wr * 64 + lane);
; #pragma unroll
;         for (int ai = 0; ai < 2; ++ai)
; #pragma unroll
;             for (int m = 0; m < 4; ++m) { const int row = row0 + ai * HALF + m * 16; const float rs = __shfl(ai ? rsl1 : rsl0, m * 16 + fr); bf16_t* rowp = O + (size_t)row * DFF + col0;
;                 const f32x4 a0 = acc[ai][0][m][0] * rs + ba0, a1 = acc[ai][0][m][1] * rs + ba1, b0 = acc[ai][1][m][0] * rs + bb0, b1 = acc[ai][1][m][1] * rs + bb1;
;                 u32x4 w; w.x = cvt_pk_bf16(silu_mul(a0[0], b0[0]), silu_mul(a0[1], b0[1])); w.y = cvt_pk_bf16(silu_mul(a0[2], b0[2]), silu_mul(a0[3], b0[3]));
;                 w.z = cvt_pk_bf16(silu_mul(a1[0], b1[0]), silu_mul(a1[1], b1[1])); w.w = cvt_pk_bf16(silu_mul(a1[2], b1[2]), silu_mul(a1[3], b1[3]));
;                 *(u32x4*)rowp = w; }
.LBB0_2921:
	s_lshl_b32 s2, s2, 8
	s_add_i32 s11, s2, s34
	s_lshl_b64 s[18:19], s[18:19], 2
	s_add_u32 s13, s35, s18
	s_addc_u32 s18, s38, s19
	s_lshl_b32 s2, s3, 8
	v_lshl_or_b32 v164, s3, 7, v172
	s_ashr_i32 s3, s2, 31
	s_lshl_b64 s[2:3], s[2:3], 2
	s_add_u32 s2, s13, s2
	s_addc_u32 s3, s18, s3
	v_or_b32_e32 v162, s11, v170
	s_add_u32 s2, s2, s44
	v_ashrrev_i32_e32 v163, 31, v162
	s_addc_u32 s3, s3, 0
	v_lshl_add_u64 v[162:163], v[162:163], 2, s[0:1]
	v_mov_b32_e32 v74, v234
	v_mov_b32_e32 v75, v235
	v_mov_b32_e32 v76, v236
	v_mov_b32_e32 v77, v237
	v_mov_b32_e32 v78, v238
	v_mov_b32_e32 v79, v239
	v_mov_b32_e32 v80, v240
	v_mov_b32_e32 v81, v241
	v_mov_b32_e32 v66, v242
	v_mov_b32_e32 v67, v243
	v_mov_b32_e32 v68, v244
	v_mov_b32_e32 v69, v245
	v_mov_b32_e32 v70, v246
	v_mov_b32_e32 v71, v247
	v_mov_b32_e32 v72, v248
	v_mov_b32_e32 v73, v249
	v_or_b32_e32 v180, s11, v1
	v_mov_b32_e32 v162, v250
	s_waitcnt vmcnt(0)
	v_fmamk_f32 v162, v162, 0x3a000000, v177
	v_cmp_gt_f32_e32 vcc, s45, v162
	v_mul_f32_e32 v163, 0x4f800000, v162
	s_nop 0
	v_cndmask_b32_e32 v162, v162, v163, vcc
	v_sqrt_f32_e32 v163, v162
	s_nop 0
	v_add_u32_e32 v165, -1, v163
	v_fma_f32 v166, -v165, v163, v162
	v_cmp_ge_f32_e64 s[2:3], 0, v166
	v_add_u32_e32 v166, 1, v163
	s_nop 0
	v_cndmask_b32_e64 v165, v163, v165, s[2:3]
	v_fma_f32 v163, -v166, v163, v162
	v_cmp_lt_f32_e64 s[2:3], 0, v163
	s_nop 1
	v_cndmask_b32_e64 v163, v165, v166, s[2:3]
	v_mul_f32_e32 v165, 0x37800000, v163
	v_cndmask_b32_e32 v163, v163, v165, vcc
	v_cmp_class_f32_e32 vcc, v162, v178
	s_nop 1
	v_cndmask_b32_e32 v166, v163, v162, vcc
	v_add_u32_e32 v162, s11, v171
	v_ashrrev_i32_e32 v163, 31, v162
	v_lshl_add_u64 v[162:163], v[162:163], 2, s[0:1]
	v_mov_b32_e32 v162, v251
	v_fmamk_f32 v162, v162, 0x3a000000, v177
	v_cmp_gt_f32_e32 vcc, s45, v162
	v_mul_f32_e32 v163, 0x4f800000, v162
	s_nop 0
	v_cndmask_b32_e32 v162, v162, v163, vcc
	v_sqrt_f32_e32 v163, v162
	s_nop 0
	v_add_u32_e32 v165, -1, v163
	v_fma_f32 v167, -v165, v163, v162
	v_cmp_ge_f32_e64 s[2:3], 0, v167
	v_add_u32_e32 v167, 1, v163
	s_nop 0
	v_cndmask_b32_e64 v165, v163, v165, s[2:3]
	v_fma_f32 v163, -v167, v163, v162
	v_cmp_lt_f32_e64 s[2:3], 0, v163
	s_nop 1
	v_cndmask_b32_e64 v163, v165, v167, s[2:3]
	v_mul_f32_e32 v165, 0x37800000, v163
	v_cndmask_b32_e32 v163, v163, v165, vcc
	v_cmp_class_f32_e32 vcc, v162, v178
	v_ashrrev_i32_e32 v165, 31, v164
	v_lshlrev_b64 v[164:165], 1, v[164:165]
	v_cndmask_b32_e32 v181, v163, v162, vcc
	v_div_scale_f32 v162, s[2:3], v166, v166, 1.0
	v_rcp_f32_e32 v163, v162
	s_nop 0
	v_fma_f32 v167, -v162, v163, 1.0
	v_fmac_f32_e32 v163, v167, v163
	v_div_scale_f32 v167, vcc, 1.0, v166, 1.0
	v_mul_f32_e32 v168, v167, v163
	v_fma_f32 v182, -v162, v168, v167
	v_fmac_f32_e32 v168, v182, v163
	v_fma_f32 v162, -v162, v168, v167
	v_div_fmas_f32 v162, v162, v163, v168
	v_div_fixup_f32 v182, v162, v166, 1.0
	s_mov_b32 s100, 0xbfb8aa3b
	ds_bpermute_b32 v168, v179, v182
	v_mov_b64_e32 v[162:163], s[96:97]
	v_mad_i64_i32 v[166:167], s[2:3], v180, s43, v[162:163]
	v_lshl_add_u64 v[166:167], v[166:167], 0, v[164:165]
	s_waitcnt lgkmcnt(0)
	v_pk_fma_f32 v[142:143], v[142:143], v[168:169], v[78:79] op_sel_hi:[1,0,1]
	v_pk_fma_f32 v[144:145], v[144:145], v[168:169], v[80:81] op_sel_hi:[1,0,1]
	v_pk_fma_f32 v[134:135], v[134:135], v[168:169], v[70:71] op_sel_hi:[1,0,1]
	v_pk_fma_f32 v[136:137], v[136:137], v[168:169], v[72:73] op_sel_hi:[1,0,1]
	v_pk_fma_f32 v[138:139], v[138:139], v[168:169], v[74:75] op_sel_hi:[1,0,1]
	v_pk_fma_f32 v[140:141], v[140:141], v[168:169], v[76:77] op_sel_hi:[1,0,1]
	v_pk_fma_f32 v[130:131], v[130:131], v[168:169], v[66:67] op_sel_hi:[1,0,1]
	v_pk_fma_f32 v[132:133], v[132:133], v[168:169], v[68:69] op_sel_hi:[1,0,1]
	v_pk_mul_f32 v[234:235], v[142:143], s[100:101] op_sel_hi:[1,0]
	v_pk_mul_f32 v[236:237], v[144:145], s[100:101] op_sel_hi:[1,0]
	v_exp_f32_e32 v234, v234
	v_exp_f32_e32 v235, v235
	v_exp_f32_e32 v236, v236
	v_exp_f32_e32 v237, v237
	v_pk_add_f32 v[234:235], v[234:235], 1.0 op_sel_hi:[1,0]
	v_pk_add_f32 v[236:237], v[236:237], 1.0 op_sel_hi:[1,0]
	v_rcp_f32_e32 v234, v234
	v_rcp_f32_e32 v235, v235
	v_rcp_f32_e32 v236, v236
	v_rcp_f32_e32 v237, v237
	v_pk_mul_f32 v[134:135], v[142:143], v[134:135]
	v_pk_mul_f32 v[136:137], v[144:145], v[136:137]
	v_pk_mul_f32 v[134:135], v[134:135], v[234:235]
	v_pk_mul_f32 v[136:137], v[136:137], v[236:237]
	v_cvt_pk_bf16_f32 v238, v134, v135
	v_cvt_pk_bf16_f32 v239, v136, v137
	v_pk_mul_f32 v[234:235], v[138:139], s[100:101] op_sel_hi:[1,0]
	v_pk_mul_f32 v[236:237], v[140:141], s[100:101] op_sel_hi:[1,0]
	v_exp_f32_e32 v234, v234
	v_exp_f32_e32 v235, v235
	v_exp_f32_e32 v236, v236
	v_exp_f32_e32 v237, v237
	v_pk_add_f32 v[234:235], v[234:235], 1.0 op_sel_hi:[1,0]
	v_pk_add_f32 v[236:237], v[236:237], 1.0 op_sel_hi:[1,0]
	v_rcp_f32_e32 v234, v234
	v_rcp_f32_e32 v235, v235
	v_rcp_f32_e32 v236, v236
	v_rcp_f32_e32 v237, v237
	v_pk_mul_f32 v[130:131], v[138:139], v[130:131]
	v_pk_mul_f32 v[132:133], v[140:141], v[132:133]
	v_pk_mul_f32 v[130:131], v[130:131], v[234:235]
	v_pk_mul_f32 v[132:133], v[132:133], v[236:237]
	v_cvt_pk_bf16_f32 v240, v130, v131
	v_cvt_pk_bf16_f32 v241, v132, v133
	global_store_dwordx4 v[166:167], v[238:241], off
	ds_bpermute_b32 v130, v179, v182 offset:64
	v_or_b32_e32 v131, 16, v180
	v_mad_i64_i32 v[132:133], s[2:3], v131, s43, v[162:163]
	s_waitcnt lgkmcnt(0)
; __device__ __forceinline__ unsigned cvt_pk_bf16(float lo, float hi) { unsigned r; asm volatile("v_cvt_pk_bf16_f32 %0, %1, %2" : "=v"(r) : "v"(lo), "v"(hi)); return r; }
; __device__ __forceinline__ float silu_mul(float a, float b) { return a * b * __builtin_amdgcn_rcpf(1.0f + __builtin_amdgcn_exp2f(-a * LOG2E)); }
;     __device__ __forceinline__ void operator()(const f32x4 (&acc)[2][2][4][2], const Unit& u, int wr, int wc, int fr, int fq) const {
;     ...
;             for (int m = 0; m < 4; ++m) { const int row = row0 + ai * HALF + m * 16; const float rs = __shfl(ai ? rsl1 : rsl0, m * 16 + fr); bf16_t* rowp = O + (size_t)row * DFF + col0;
;                 const f32x4 a0 = acc[ai][0][m][0] * rs + ba0, a1 = acc[ai][0][m][1] * rs + ba1, b0 = acc[ai][1][m][0] * rs + bb0, b1 = acc[ai][1][m][1] * rs + bb1;
;                 u32x4 w; w.x = cvt_pk_bf16(silu_mul(a0[0], b0[0]), silu_mul(a0[1], b0[1])); w.y = cvt_pk_bf16(silu_mul(a0[2], b0[2]), silu_mul(a0[3], b0[3]));
;                 w.z = cvt_pk_bf16(silu_mul(a1[0], b1[0]), silu_mul(a1[1], b1[1])); w.w = cvt_pk_bf16(silu_mul(a1[2], b1[2]), silu_mul(a1[3], b1[3]));
;                 *(u32x4*)rowp = w; }
	v_lshl_add_u64 v[132:133], v[132:133], 0, v[164:165]
	v_pk_fma_f32 v[126:127], v[126:127], v[130:131], v[78:79] op_sel_hi:[1,0,1]
	v_pk_fma_f32 v[128:129], v[128:129], v[130:131], v[80:81] op_sel_hi:[1,0,1]
	v_pk_fma_f32 v[118:119], v[118:119], v[130:131], v[70:71] op_sel_hi:[1,0,1]
	v_pk_fma_f32 v[120:121], v[120:121], v[130:131], v[72:73] op_sel_hi:[1,0,1]
	v_pk_fma_f32 v[122:123], v[122:123], v[130:131], v[74:75] op_sel_hi:[1,0,1]
	v_pk_fma_f32 v[124:125], v[124:125], v[130:131], v[76:77] op_sel_hi:[1,0,1]
	v_pk_fma_f32 v[114:115], v[114:115], v[130:131], v[66:67] op_sel_hi:[1,0,1]
	v_pk_fma_f32 v[116:117], v[116:117], v[130:131], v[68:69] op_sel_hi:[1,0,1]
	v_pk_mul_f32 v[234:235], v[126:127], s[100:101] op_sel_hi:[1,0]
	v_pk_mul_f32 v[236:237], v[128:129], s[100:101] op_sel_hi:[1,0]
	v_exp_f32_e32 v234, v234
	v_exp_f32_e32 v235, v235
	v_exp_f32_e32 v236, v236
	v_exp_f32_e32 v237, v237
	v_pk_add_f32 v[234:235], v[234:235], 1.0 op_sel_hi:[1,0]
	v_pk_add_f32 v[236:237], v[236:237], 1.0 op_sel_hi:[1,0]
	v_rcp_f32_e32 v234, v234
	v_rcp_f32_e32 v235, v235
	v_rcp_f32_e32 v236, v236
	v_rcp_f32_e32 v237, v237
	v_pk_mul_f32 v[118:119], v[126:127], v[118:119]
	v_pk_mul_f32 v[120:121], v[128:129], v[120:121]
	v_pk_mul_f32 v[118:119], v[118:119], v[234:235]
	v_pk_mul_f32 v[120:121], v[120:121], v[236:237]
	v_cvt_pk_bf16_f32 v238, v118, v119
	v_cvt_pk_bf16_f32 v239, v120, v121
	v_pk_mul_f32 v[234:235], v[122:123], s[100:101] op_sel_hi:[1,0]
	v_pk_mul_f32 v[236:237], v[124:125], s[100:101] op_sel_hi:[1,0]
	v_exp_f32_e32 v234, v234
	v_exp_f32_e32 v235, v235
	v_exp_f32_e32 v236, v236
	v_exp_f32_e32 v237, v237
	v_pk_add_f32 v[234:235], v[234:235], 1.0 op_sel_hi:[1,0]
	v_pk_add_f32 v[236:237], v[236:237], 1.0 op_sel_hi:[1,0]
	v_rcp_f32_e32 v234, v234
	v_rcp_f32_e32 v235, v235
	v_rcp_f32_e32 v236, v236
	v_rcp_f32_e32 v237, v237
	v_pk_mul_f32 v[114:115], v[122:123], v[114:115]
	v_pk_mul_f32 v[116:117], v[124:125], v[116:117]
	v_pk_mul_f32 v[114:115], v[114:115], v[234:235]
	v_pk_mul_f32 v[116:117], v[116:117], v[236:237]
	v_cvt_pk_bf16_f32 v240, v114, v115
	v_cvt_pk_bf16_f32 v241, v116, v117
	global_store_dwordx4 v[132:133], v[238:241], off
	ds_bpermute_b32 v114, v179, v182 offset:128
	v_or_b32_e32 v115, 32, v180
	v_mad_i64_i32 v[116:117], s[2:3], v115, s43, v[162:163]
	s_waitcnt lgkmcnt(0)
	v_lshl_add_u64 v[116:117], v[116:117], 0, v[164:165]
	v_pk_fma_f32 v[110:111], v[110:111], v[114:115], v[78:79] op_sel_hi:[1,0,1]
	v_pk_fma_f32 v[112:113], v[112:113], v[114:115], v[80:81] op_sel_hi:[1,0,1]
	v_pk_fma_f32 v[102:103], v[102:103], v[114:115], v[70:71] op_sel_hi:[1,0,1]
	v_pk_fma_f32 v[104:105], v[104:105], v[114:115], v[72:73] op_sel_hi:[1,0,1]
	v_pk_fma_f32 v[106:107], v[106:107], v[114:115], v[74:75] op_sel_hi:[1,0,1]
	v_pk_fma_f32 v[108:109], v[108:109], v[114:115], v[76:77] op_sel_hi:[1,0,1]
	v_pk_fma_f32 v[98:99], v[98:99], v[114:115], v[66:67] op_sel_hi:[1,0,1]
	v_pk_fma_f32 v[100:101], v[100:101], v[114:115], v[68:69] op_sel_hi:[1,0,1]
	v_pk_mul_f32 v[234:235], v[110:111], s[100:101] op_sel_hi:[1,0]
	v_pk_mul_f32 v[236:237], v[112:113], s[100:101] op_sel_hi:[1,0]
	v_exp_f32_e32 v234, v234
	v_exp_f32_e32 v235, v235
	v_exp_f32_e32 v236, v236
	v_exp_f32_e32 v237, v237
	v_pk_add_f32 v[234:235], v[234:235], 1.0 op_sel_hi:[1,0]
	v_pk_add_f32 v[236:237], v[236:237], 1.0 op_sel_hi:[1,0]
	v_rcp_f32_e32 v234, v234
	v_rcp_f32_e32 v235, v235
	v_rcp_f32_e32 v236, v236
	v_rcp_f32_e32 v237, v237
	v_pk_mul_f32 v[102:103], v[110:111], v[102:103]
	v_pk_mul_f32 v[104:105], v[112:113], v[104:105]
	v_pk_mul_f32 v[102:103], v[102:103], v[234:235]
	v_pk_mul_f32 v[104:105], v[104:105], v[236:237]
	v_cvt_pk_bf16_f32 v238, v102, v103
	v_cvt_pk_bf16_f32 v239, v104, v105
	v_pk_mul_f32 v[234:235], v[106:107], s[100:101] op_sel_hi:[1,0]
	v_pk_mul_f32 v[236:237], v[108:109], s[100:101] op_sel_hi:[1,0]
	v_exp_f32_e32 v234, v234
	v_exp_f32_e32 v235, v235
	v_exp_f32_e32 v236, v236
	v_exp_f32_e32 v237, v237
	v_pk_add_f32 v[234:235], v[234:235], 1.0 op_sel_hi:[1,0]
	v_pk_add_f32 v[236:237], v[236:237], 1.0 op_sel_hi:[1,0]
	v_rcp_f32_e32 v234, v234
	v_rcp_f32_e32 v235, v235
	v_rcp_f32_e32 v236, v236
	v_rcp_f32_e32 v237, v237
	v_pk_mul_f32 v[98:99], v[106:107], v[98:99]
	v_pk_mul_f32 v[100:101], v[108:109], v[100:101]
	v_pk_mul_f32 v[98:99], v[98:99], v[234:235]
	v_pk_mul_f32 v[100:101], v[100:101], v[236:237]
	v_cvt_pk_bf16_f32 v240, v98, v99
	v_cvt_pk_bf16_f32 v241, v100, v101
	global_store_dwordx4 v[116:117], v[238:241], off
	ds_bpermute_b32 v98, v179, v182 offset:192
	v_or_b32_e32 v99, 48, v180
	v_mad_i64_i32 v[100:101], s[2:3], v99, s43, v[162:163]
	s_waitcnt lgkmcnt(0)
; __device__ __forceinline__ unsigned cvt_pk_bf16(float lo, float hi) { unsigned r; asm volatile("v_cvt_pk_bf16_f32 %0, %1, %2" : "=v"(r) : "v"(lo), "v"(hi)); return r; }
; __device__ __forceinline__ float row_rstd(const float* ss, int row) { return 1.0f / sqrtf(ss[row] * (1.0f / DM) + 1e-6f); }
; __device__ __forceinline__ float silu_mul(float a, float b) { return a * b * __builtin_amdgcn_rcpf(1.0f + __builtin_amdgcn_exp2f(-a * LOG2E)); }
;     __device__ __forceinline__ void operator()(const f32x4 (&acc)[2][2][4][2], const Unit& u, int wr, int wc, int fr, int fq) const {
;     ...
;         const float rsl0 = row_rstd(ss, u.pm * BM + wr * 64 + lane), rsl1 = row_rstd(ss, u.pm * BM + HALF + wr * 64 + lane);
; #pragma unroll
;         for (int ai = 0; ai < 2; ++ai)
; #pragma unroll
;             for (int m = 0; m < 4; ++m) { const int row = row0 + ai * HALF + m * 16; const float rs = __shfl(ai ? rsl1 : rsl0, m * 16 + fr); bf16_t* rowp = O + (size_t)row * DFF + col0;
;                 const f32x4 a0 = acc[ai][0][m][0] * rs + ba0, a1 = acc[ai][0][m][1] * rs + ba1, b0 = acc[ai][1][m][0] * rs + bb0, b1 = acc[ai][1][m][1] * rs + bb1;
;                 u32x4 w; w.x = cvt_pk_bf16(silu_mul(a0[0], b0[0]), silu_mul(a0[1], b0[1])); w.y = cvt_pk_bf16(silu_mul(a0[2], b0[2]), silu_mul(a0[3], b0[3]));
;                 w.z = cvt_pk_bf16(silu_mul(a1[0], b1[0]), silu_mul(a1[1], b1[1])); w.w = cvt_pk_bf16(silu_mul(a1[2], b1[2]), silu_mul(a1[3], b1[3]));
;                 *(u32x4*)rowp = w; }
	v_lshl_add_u64 v[100:101], v[100:101], 0, v[164:165]
	v_pk_fma_f32 v[94:95], v[94:95], v[98:99], v[78:79] op_sel_hi:[1,0,1]
	v_pk_fma_f32 v[96:97], v[96:97], v[98:99], v[80:81] op_sel_hi:[1,0,1]
	v_pk_fma_f32 v[86:87], v[86:87], v[98:99], v[70:71] op_sel_hi:[1,0,1]
	v_pk_fma_f32 v[88:89], v[88:89], v[98:99], v[72:73] op_sel_hi:[1,0,1]
	v_pk_fma_f32 v[90:91], v[90:91], v[98:99], v[74:75] op_sel_hi:[1,0,1]
	v_pk_fma_f32 v[92:93], v[92:93], v[98:99], v[76:77] op_sel_hi:[1,0,1]
	v_pk_fma_f32 v[82:83], v[82:83], v[98:99], v[66:67] op_sel_hi:[1,0,1]
	v_pk_fma_f32 v[84:85], v[84:85], v[98:99], v[68:69] op_sel_hi:[1,0,1]
	v_pk_mul_f32 v[234:235], v[94:95], s[100:101] op_sel_hi:[1,0]
	v_pk_mul_f32 v[236:237], v[96:97], s[100:101] op_sel_hi:[1,0]
	v_exp_f32_e32 v234, v234
	v_exp_f32_e32 v235, v235
	v_exp_f32_e32 v236, v236
	v_exp_f32_e32 v237, v237
	v_pk_add_f32 v[234:235], v[234:235], 1.0 op_sel_hi:[1,0]
	v_pk_add_f32 v[236:237], v[236:237], 1.0 op_sel_hi:[1,0]
	v_rcp_f32_e32 v234, v234
	v_rcp_f32_e32 v235, v235
	v_rcp_f32_e32 v236, v236
	v_rcp_f32_e32 v237, v237
	v_pk_mul_f32 v[86:87], v[94:95], v[86:87]
	v_pk_mul_f32 v[88:89], v[96:97], v[88:89]
	v_pk_mul_f32 v[86:87], v[86:87], v[234:235]
	v_pk_mul_f32 v[88:89], v[88:89], v[236:237]
	v_cvt_pk_bf16_f32 v238, v86, v87
	v_cvt_pk_bf16_f32 v239, v88, v89
	v_pk_mul_f32 v[234:235], v[90:91], s[100:101] op_sel_hi:[1,0]
	v_pk_mul_f32 v[236:237], v[92:93], s[100:101] op_sel_hi:[1,0]
	v_exp_f32_e32 v234, v234
	v_exp_f32_e32 v235, v235
	v_exp_f32_e32 v236, v236
	v_exp_f32_e32 v237, v237
	v_pk_add_f32 v[234:235], v[234:235], 1.0 op_sel_hi:[1,0]
	v_pk_add_f32 v[236:237], v[236:237], 1.0 op_sel_hi:[1,0]
	v_rcp_f32_e32 v234, v234
	v_rcp_f32_e32 v235, v235
	v_rcp_f32_e32 v236, v236
	v_rcp_f32_e32 v237, v237
	v_pk_mul_f32 v[82:83], v[90:91], v[82:83]
	v_pk_mul_f32 v[84:85], v[92:93], v[84:85]
	v_pk_mul_f32 v[82:83], v[82:83], v[234:235]
	v_pk_mul_f32 v[84:85], v[84:85], v[236:237]
	v_cvt_pk_bf16_f32 v240, v82, v83
	v_cvt_pk_bf16_f32 v241, v84, v85
	global_store_dwordx4 v[100:101], v[238:241], off
	s_nop 1
	v_div_scale_f32 v82, s[2:3], v181, v181, 1.0
	v_rcp_f32_e32 v84, v82
	v_add_u32_e32 v83, 0x80, v180
	v_fma_f32 v85, -v82, v84, 1.0
	v_fmac_f32_e32 v84, v85, v84
	v_div_scale_f32 v85, vcc, 1.0, v181, 1.0
	v_mul_f32_e32 v86, v85, v84
	v_fma_f32 v87, -v82, v86, v85
	v_fmac_f32_e32 v86, v87, v84
	v_fma_f32 v82, -v82, v86, v85
	v_div_fmas_f32 v82, v82, v84, v86
	v_div_fixup_f32 v82, v82, v181, 1.0
	ds_bpermute_b32 v84, v179, v82
	v_mad_i64_i32 v[86:87], s[2:3], v83, s43, v[162:163]
	v_lshl_add_u64 v[86:87], v[86:87], 0, v[164:165]
	s_and_b64 vcc, s[36:37], exec
	s_waitcnt lgkmcnt(0)
	v_pk_fma_f32 v[62:63], v[62:63], v[84:85], v[78:79] op_sel_hi:[1,0,1]
	v_pk_fma_f32 v[64:65], v[64:65], v[84:85], v[80:81] op_sel_hi:[1,0,1]
	v_pk_fma_f32 v[54:55], v[54:55], v[84:85], v[70:71] op_sel_hi:[1,0,1]
	v_pk_fma_f32 v[56:57], v[56:57], v[84:85], v[72:73] op_sel_hi:[1,0,1]
	v_pk_fma_f32 v[58:59], v[58:59], v[84:85], v[74:75] op_sel_hi:[1,0,1]
	v_pk_fma_f32 v[60:61], v[60:61], v[84:85], v[76:77] op_sel_hi:[1,0,1]
	v_pk_fma_f32 v[50:51], v[50:51], v[84:85], v[66:67] op_sel_hi:[1,0,1]
	v_pk_fma_f32 v[52:53], v[52:53], v[84:85], v[68:69] op_sel_hi:[1,0,1]
	v_pk_mul_f32 v[234:235], v[62:63], s[100:101] op_sel_hi:[1,0]
	v_pk_mul_f32 v[236:237], v[64:65], s[100:101] op_sel_hi:[1,0]
	v_exp_f32_e32 v234, v234
	v_exp_f32_e32 v235, v235
	v_exp_f32_e32 v236, v236
	v_exp_f32_e32 v237, v237
	v_pk_add_f32 v[234:235], v[234:235], 1.0 op_sel_hi:[1,0]
	v_pk_add_f32 v[236:237], v[236:237], 1.0 op_sel_hi:[1,0]
	v_rcp_f32_e32 v234, v234
	v_rcp_f32_e32 v235, v235
	v_rcp_f32_e32 v236, v236
	v_rcp_f32_e32 v237, v237
	v_pk_mul_f32 v[54:55], v[62:63], v[54:55]
	v_pk_mul_f32 v[56:57], v[64:65], v[56:57]
	v_pk_mul_f32 v[54:55], v[54:55], v[234:235]
	v_pk_mul_f32 v[56:57], v[56:57], v[236:237]
	v_cvt_pk_bf16_f32 v238, v54, v55
	v_cvt_pk_bf16_f32 v239, v56, v57
	v_pk_mul_f32 v[234:235], v[58:59], s[100:101] op_sel_hi:[1,0]
	v_pk_mul_f32 v[236:237], v[60:61], s[100:101] op_sel_hi:[1,0]
	v_exp_f32_e32 v234, v234
	v_exp_f32_e32 v235, v235
	v_exp_f32_e32 v236, v236
	v_exp_f32_e32 v237, v237
	v_pk_add_f32 v[234:235], v[234:235], 1.0 op_sel_hi:[1,0]
	v_pk_add_f32 v[236:237], v[236:237], 1.0 op_sel_hi:[1,0]
	v_rcp_f32_e32 v234, v234
	v_rcp_f32_e32 v235, v235
	v_rcp_f32_e32 v236, v236
	v_rcp_f32_e32 v237, v237
	v_pk_mul_f32 v[50:51], v[58:59], v[50:51]
	v_pk_mul_f32 v[52:53], v[60:61], v[52:53]
	v_pk_mul_f32 v[50:51], v[50:51], v[234:235]
	v_pk_mul_f32 v[52:53], v[52:53], v[236:237]
	v_cvt_pk_bf16_f32 v240, v50, v51
	v_cvt_pk_bf16_f32 v241, v52, v53
	global_store_dwordx4 v[86:87], v[238:241], off
	ds_bpermute_b32 v50, v179, v82 offset:64
	v_add_u32_e32 v51, 0x90, v180
	v_mad_i64_i32 v[52:53], s[2:3], v51, s43, v[162:163]
	s_waitcnt lgkmcnt(0)
; __device__ __forceinline__ unsigned cvt_pk_bf16(float lo, float hi) { unsigned r; asm volatile("v_cvt_pk_bf16_f32 %0, %1, %2" : "=v"(r) : "v"(lo), "v"(hi)); return r; }
; __device__ __forceinline__ float silu_mul(float a, float b) { return a * b * __builtin_amdgcn_rcpf(1.0f + __builtin_amdgcn_exp2f(-a * LOG2E)); }
;     __device__ __forceinline__ void operator()(const f32x4 (&acc)[2][2][4][2], const Unit& u, int wr, int wc, int fr, int fq) const {
;     ...
;             for (int m = 0; m < 4; ++m) { const int row = row0 + ai * HALF + m * 16; const float rs = __shfl(ai ? rsl1 : rsl0, m * 16 + fr); bf16_t* rowp = O + (size_t)row * DFF + col0;
;                 const f32x4 a0 = acc[ai][0][m][0] * rs + ba0, a1 = acc[ai][0][m][1] * rs + ba1, b0 = acc[ai][1][m][0] * rs + bb0, b1 = acc[ai][1][m][1] * rs + bb1;
;                 u32x4 w; w.x = cvt_pk_bf16(silu_mul(a0[0], b0[0]), silu_mul(a0[1], b0[1])); w.y = cvt_pk_bf16(silu_mul(a0[2], b0[2]), silu_mul(a0[3], b0[3]));
;                 w.z = cvt_pk_bf16(silu_mul(a1[0], b1[0]), silu_mul(a1[1], b1[1])); w.w = cvt_pk_bf16(silu_mul(a1[2], b1[2]), silu_mul(a1[3], b1[3]));
;                 *(u32x4*)rowp = w; }
	v_lshl_add_u64 v[52:53], v[52:53], 0, v[164:165]
	v_pk_fma_f32 v[46:47], v[46:47], v[50:51], v[78:79] op_sel_hi:[1,0,1]
	v_pk_fma_f32 v[48:49], v[48:49], v[50:51], v[80:81] op_sel_hi:[1,0,1]
	v_pk_fma_f32 v[38:39], v[38:39], v[50:51], v[70:71] op_sel_hi:[1,0,1]
	v_pk_fma_f32 v[40:41], v[40:41], v[50:51], v[72:73] op_sel_hi:[1,0,1]
	v_pk_fma_f32 v[42:43], v[42:43], v[50:51], v[74:75] op_sel_hi:[1,0,1]
	v_pk_fma_f32 v[44:45], v[44:45], v[50:51], v[76:77] op_sel_hi:[1,0,1]
	v_pk_fma_f32 v[34:35], v[34:35], v[50:51], v[66:67] op_sel_hi:[1,0,1]
	v_pk_fma_f32 v[36:37], v[36:37], v[50:51], v[68:69] op_sel_hi:[1,0,1]
	v_pk_mul_f32 v[234:235], v[46:47], s[100:101] op_sel_hi:[1,0]
	v_pk_mul_f32 v[236:237], v[48:49], s[100:101] op_sel_hi:[1,0]
	v_exp_f32_e32 v234, v234
	v_exp_f32_e32 v235, v235
	v_exp_f32_e32 v236, v236
	v_exp_f32_e32 v237, v237
	v_pk_add_f32 v[234:235], v[234:235], 1.0 op_sel_hi:[1,0]
	v_pk_add_f32 v[236:237], v[236:237], 1.0 op_sel_hi:[1,0]
	v_rcp_f32_e32 v234, v234
	v_rcp_f32_e32 v235, v235
	v_rcp_f32_e32 v236, v236
	v_rcp_f32_e32 v237, v237
	v_pk_mul_f32 v[38:39], v[46:47], v[38:39]
	v_pk_mul_f32 v[40:41], v[48:49], v[40:41]
	v_pk_mul_f32 v[38:39], v[38:39], v[234:235]
	v_pk_mul_f32 v[40:41], v[40:41], v[236:237]
	v_cvt_pk_bf16_f32 v238, v38, v39
	v_cvt_pk_bf16_f32 v239, v40, v41
	v_pk_mul_f32 v[234:235], v[42:43], s[100:101] op_sel_hi:[1,0]
	v_pk_mul_f32 v[236:237], v[44:45], s[100:101] op_sel_hi:[1,0]
	v_exp_f32_e32 v234, v234
	v_exp_f32_e32 v235, v235
	v_exp_f32_e32 v236, v236
	v_exp_f32_e32 v237, v237
	v_pk_add_f32 v[234:235], v[234:235], 1.0 op_sel_hi:[1,0]
	v_pk_add_f32 v[236:237], v[236:237], 1.0 op_sel_hi:[1,0]
	v_rcp_f32_e32 v234, v234
	v_rcp_f32_e32 v235, v235
	v_rcp_f32_e32 v236, v236
	v_rcp_f32_e32 v237, v237
	v_pk_mul_f32 v[34:35], v[42:43], v[34:35]
	v_pk_mul_f32 v[36:37], v[44:45], v[36:37]
	v_pk_mul_f32 v[34:35], v[34:35], v[234:235]
	v_pk_mul_f32 v[36:37], v[36:37], v[236:237]
	v_cvt_pk_bf16_f32 v240, v34, v35
	v_cvt_pk_bf16_f32 v241, v36, v37
	global_store_dwordx4 v[52:53], v[238:241], off
	ds_bpermute_b32 v34, v179, v82 offset:128
	v_add_u32_e32 v35, 0xa0, v180
	v_mad_i64_i32 v[36:37], s[2:3], v35, s43, v[162:163]
	s_waitcnt lgkmcnt(0)
	v_lshl_add_u64 v[36:37], v[36:37], 0, v[164:165]
	v_pk_fma_f32 v[30:31], v[30:31], v[34:35], v[78:79] op_sel_hi:[1,0,1]
	v_pk_fma_f32 v[32:33], v[32:33], v[34:35], v[80:81] op_sel_hi:[1,0,1]
	v_pk_fma_f32 v[22:23], v[22:23], v[34:35], v[70:71] op_sel_hi:[1,0,1]
	v_pk_fma_f32 v[24:25], v[24:25], v[34:35], v[72:73] op_sel_hi:[1,0,1]
	v_pk_fma_f32 v[26:27], v[26:27], v[34:35], v[74:75] op_sel_hi:[1,0,1]
	v_pk_fma_f32 v[28:29], v[28:29], v[34:35], v[76:77] op_sel_hi:[1,0,1]
	v_pk_fma_f32 v[18:19], v[18:19], v[34:35], v[66:67] op_sel_hi:[1,0,1]
	v_pk_fma_f32 v[20:21], v[20:21], v[34:35], v[68:69] op_sel_hi:[1,0,1]
	v_pk_mul_f32 v[234:235], v[30:31], s[100:101] op_sel_hi:[1,0]
	v_pk_mul_f32 v[236:237], v[32:33], s[100:101] op_sel_hi:[1,0]
	v_exp_f32_e32 v234, v234
	v_exp_f32_e32 v235, v235
	v_exp_f32_e32 v236, v236
	v_exp_f32_e32 v237, v237
	v_pk_add_f32 v[234:235], v[234:235], 1.0 op_sel_hi:[1,0]
	v_pk_add_f32 v[236:237], v[236:237], 1.0 op_sel_hi:[1,0]
	v_rcp_f32_e32 v234, v234
	v_rcp_f32_e32 v235, v235
	v_rcp_f32_e32 v236, v236
	v_rcp_f32_e32 v237, v237
	v_pk_mul_f32 v[22:23], v[30:31], v[22:23]
	v_pk_mul_f32 v[24:25], v[32:33], v[24:25]
	v_pk_mul_f32 v[22:23], v[22:23], v[234:235]
	v_pk_mul_f32 v[24:25], v[24:25], v[236:237]
	v_cvt_pk_bf16_f32 v238, v22, v23
	v_cvt_pk_bf16_f32 v239, v24, v25
	v_pk_mul_f32 v[234:235], v[26:27], s[100:101] op_sel_hi:[1,0]
	v_pk_mul_f32 v[236:237], v[28:29], s[100:101] op_sel_hi:[1,0]
	v_exp_f32_e32 v234, v234
	v_exp_f32_e32 v235, v235
	v_exp_f32_e32 v236, v236
	v_exp_f32_e32 v237, v237
	v_pk_add_f32 v[234:235], v[234:235], 1.0 op_sel_hi:[1,0]
	v_pk_add_f32 v[236:237], v[236:237], 1.0 op_sel_hi:[1,0]
	v_rcp_f32_e32 v234, v234
	v_rcp_f32_e32 v235, v235
	v_rcp_f32_e32 v236, v236
	v_rcp_f32_e32 v237, v237
	v_pk_mul_f32 v[18:19], v[26:27], v[18:19]
	v_pk_mul_f32 v[20:21], v[28:29], v[20:21]
	v_pk_mul_f32 v[18:19], v[18:19], v[234:235]
	v_pk_mul_f32 v[20:21], v[20:21], v[236:237]
	v_cvt_pk_bf16_f32 v240, v18, v19
	v_cvt_pk_bf16_f32 v241, v20, v21
	global_store_dwordx4 v[36:37], v[238:241], off
	ds_bpermute_b32 v18, v179, v82 offset:192
	v_add_u32_e32 v19, 0xb0, v180
	v_mad_i64_i32 v[20:21], s[2:3], v19, s43, v[162:163]
	s_waitcnt lgkmcnt(0)
	v_lshl_add_u64 v[20:21], v[20:21], 0, v[164:165]
	s_mov_b64 s[2:3], -1
	v_pk_fma_f32 v[14:15], v[14:15], v[18:19], v[78:79] op_sel_hi:[1,0,1]
	v_pk_fma_f32 v[16:17], v[16:17], v[18:19], v[80:81] op_sel_hi:[1,0,1]
	v_pk_fma_f32 v[6:7], v[6:7], v[18:19], v[70:71] op_sel_hi:[1,0,1]
	v_pk_fma_f32 v[8:9], v[8:9], v[18:19], v[72:73] op_sel_hi:[1,0,1]
	v_pk_fma_f32 v[10:11], v[10:11], v[18:19], v[74:75] op_sel_hi:[1,0,1]
	v_pk_fma_f32 v[12:13], v[12:13], v[18:19], v[76:77] op_sel_hi:[1,0,1]
	v_pk_fma_f32 v[2:3], v[2:3], v[18:19], v[66:67] op_sel_hi:[1,0,1]
	v_pk_fma_f32 v[4:5], v[4:5], v[18:19], v[68:69] op_sel_hi:[1,0,1]
	v_pk_mul_f32 v[234:235], v[14:15], s[100:101] op_sel_hi:[1,0]
	v_pk_mul_f32 v[236:237], v[16:17], s[100:101] op_sel_hi:[1,0]
	v_exp_f32_e32 v234, v234
	v_exp_f32_e32 v235, v235
	v_exp_f32_e32 v236, v236
	v_exp_f32_e32 v237, v237
	v_pk_add_f32 v[234:235], v[234:235], 1.0 op_sel_hi:[1,0]
	v_pk_add_f32 v[236:237], v[236:237], 1.0 op_sel_hi:[1,0]
	v_rcp_f32_e32 v234, v234
	v_rcp_f32_e32 v235, v235
	v_rcp_f32_e32 v236, v236
	v_rcp_f32_e32 v237, v237
	v_pk_mul_f32 v[6:7], v[14:15], v[6:7]
	v_pk_mul_f32 v[8:9], v[16:17], v[8:9]
	v_pk_mul_f32 v[6:7], v[6:7], v[234:235]
	v_pk_mul_f32 v[8:9], v[8:9], v[236:237]
	v_cvt_pk_bf16_f32 v238, v6, v7
	v_cvt_pk_bf16_f32 v239, v8, v9
	v_pk_mul_f32 v[234:235], v[10:11], s[100:101] op_sel_hi:[1,0]
	v_pk_mul_f32 v[236:237], v[12:13], s[100:101] op_sel_hi:[1,0]
	v_exp_f32_e32 v234, v234
	v_exp_f32_e32 v235, v235
	v_exp_f32_e32 v236, v236
	v_exp_f32_e32 v237, v237
	v_pk_add_f32 v[234:235], v[234:235], 1.0 op_sel_hi:[1,0]
	v_pk_add_f32 v[236:237], v[236:237], 1.0 op_sel_hi:[1,0]
	v_rcp_f32_e32 v234, v234
	v_rcp_f32_e32 v235, v235
	v_rcp_f32_e32 v236, v236
	v_rcp_f32_e32 v237, v237
	v_pk_mul_f32 v[2:3], v[10:11], v[2:3]
	v_pk_mul_f32 v[4:5], v[12:13], v[4:5]
	v_pk_mul_f32 v[2:3], v[2:3], v[234:235]
	v_pk_mul_f32 v[4:5], v[4:5], v[236:237]
	v_cvt_pk_bf16_f32 v240, v2, v3
	v_cvt_pk_bf16_f32 v241, v4, v5
	global_store_dwordx4 v[20:21], v[238:241], off
	s_cbranch_vccz .LBB0_2912
	s_andn2_b64 vcc, exec, s[4:5]
	s_cbranch_vccnz .LBB0_2911
	s_barrier
	s_branch .LBB0_2911
